# diff attention map0 loop also hand-scheduled (first-pass accumulators v0-23 parked in LDS during second pass)
# speedup vs baseline: 1.0173x; 1.0173x over previous
; #define QK0(j) ATTN_QK_STEP(sc_cur, Kc, j)
; template <bool MLA, int DK, int DV>
; __device__ __forceinline__ void attn_core(const Params& p, int b, int h, int map, int q0, int nt, char* smem,
;                                           f32x16 (&o)[DV / 32], float& lout) {
;     ...
; #pragma unroll
;   for (int sub = 0; sub < 2; ++sub)
; #pragma unroll
;     for (int i = 0; i < 16; ++i) { sc_cur[sub][i] = 0.f; sc_nxt[sub][i] = 0.f; }
;   {
;     const bft* Kc = Ks;
;     ...
;     QK0(0) QK0(1) QK0(2) QK0(3) QK0(4) QK0(5)
;     if constexpr (NKS == 6) { QK0(6) QK0(7) QK0(8) QK0(9) QK0(10) QK0(11) }
;     ...
;     float mx = -INFINITY;
; #pragma unroll
;     for (int sub = 0; sub < 2; ++sub)
; #pragma unroll
;       for (int i = 0; i < 16; ++i) mx = fmaxf(mx, sc_cur[sub][i]);
;     mx = fmaxf(mx, __shfl_xor(mx, 32));
;     mrun = mx * sc;
;   }
;   __syncthreads();
.LBB0_687:
	s_or_b64 exec, exec, s[12:13]
	v_lshlrev_b32_e32 v56, 3, v51
	v_mul_u32_u24_e32 v58, 0x68, v52
	v_lshlrev_b32_e32 v56, 1, v56
	v_lshl_add_u32 v218, v58, 1, v56
	s_waitcnt lgkmcnt(0)
	s_barrier
	ds_read_b128 v[58:61], v218
	ds_read_b128 v[62:65], v218 offset:32
	s_waitcnt vmcnt(2) lgkmcnt(1)
	v_mfma_f32_32x32x16_bf16 v[96:111], v[58:61], v[162:165], 0
	ds_read_b128 v[58:61], v218 offset:64
	s_mov_b32 s86, s65
	s_mov_b32 s87, s65
	v_mul_u32_u24_e32 v52, 0x44, v52
	s_mov_b32 s72, s65
	s_mov_b32 s73, s65
	s_mov_b32 s74, s65
	s_waitcnt vmcnt(1) lgkmcnt(1)
	v_mfma_f32_32x32x16_bf16 v[96:111], v[62:65], v[166:169], v[96:111]
	ds_read_b128 v[62:65], v218 offset:6656
	s_mov_b32 s75, s65
	s_mov_b32 s76, s65
	s_mov_b32 s77, s65
	s_mov_b32 s78, s65
	s_mov_b32 s79, s65
	s_mov_b32 s80, s65
	s_waitcnt vmcnt(0) lgkmcnt(1)
	v_mfma_f32_32x32x16_bf16 v[96:111], v[58:61], v[170:173], v[96:111]
	ds_read_b128 v[58:61], v218 offset:6688
	s_mov_b32 s81, s65
	s_mov_b32 s82, s65
	s_mov_b32 s83, s65
	s_mov_b32 s84, s65
	s_mov_b32 s85, s65
	v_mov_b64_e32 v[158:159], s[86:87]
	s_waitcnt lgkmcnt(1)
	v_mfma_f32_32x32x16_bf16 v[128:143], v[62:65], v[162:165], 0
	ds_read_b128 v[62:65], v218 offset:6720
	s_nop 1
	v_max3_f32 v56, v96, s55, v97
	v_max3_f32 v56, v56, v98, v99
	v_max3_f32 v56, v56, v100, v101
	v_max3_f32 v56, v56, v102, v103
	v_max3_f32 v56, v56, v104, v105
	v_max3_f32 v56, v56, v106, v107
	s_waitcnt lgkmcnt(1)
	v_mfma_f32_32x32x16_bf16 v[128:143], v[58:61], v[166:169], v[128:143]
	v_max3_f32 v56, v56, v108, v109
	v_max3_f32 v56, v56, v110, v111
	v_lshlrev_b32_e32 v52, 1, v52
	v_mov_b64_e32 v[156:157], s[84:85]
	v_mov_b64_e32 v[154:155], s[82:83]
	v_mov_b64_e32 v[152:153], s[80:81]
	v_mov_b64_e32 v[150:151], s[78:79]
	s_waitcnt lgkmcnt(0)
	v_mfma_f32_32x32x16_bf16 v[128:143], v[62:65], v[170:173], v[128:143]
	v_mov_b64_e32 v[148:149], s[76:77]
	v_mov_b64_e32 v[146:147], s[74:75]
	v_mov_b64_e32 v[144:145], s[72:73]
	v_lshl_add_u32 v219, v51, 3, v52
	v_lshlrev_b32_e32 v51, 1, v48
	s_movk_i32 s82, 0x88
	v_lshl_add_u64 v[190:191], v[48:49], 1, s[16:17]
	s_nop 4
	v_max3_f32 v56, v56, v128, v129
	v_max3_f32 v56, v56, v130, v131
	v_max3_f32 v56, v56, v132, v133
	v_max3_f32 v56, v56, v134, v135
	v_max3_f32 v56, v56, v136, v137
	v_max3_f32 v56, v56, v138, v139
	v_max3_f32 v56, v56, v140, v141
	v_max3_f32 v56, v56, v142, v143
	ds_bpermute_b32 v58, v215, v56
	v_add_u32_e32 v48, s38, v55
	v_mad_u64_u32 v[186:187], s[12:13], v53, s82, v[160:161]
	v_mad_u64_u32 v[188:189], s[12:13], v54, s82, v[160:161]
	s_waitcnt lgkmcnt(0)
	v_max_f32_e32 v58, v58, v58
	v_add_u32_e32 v160, 0xc0, v48
	v_lshlrev_b32_e32 v48, 4, v50
	v_max_f32_e32 v56, v56, v58
	v_mad_i64_i32 v[58:59], s[12:13], v53, s54, 0
	v_mad_i64_i32 v[60:61], s[12:13], v54, s54, 0
	v_and_b32_e32 v48, 0x70, v48
	v_or_b32_e32 v58, v58, v48
	v_or_b32_e32 v60, v60, v48
	v_mov_b32_e32 v187, 0
	v_mov_b64_e32 v[112:113], v[144:145]
	v_mul_f32_e32 v221, 1.0, v56
	s_mov_b32 s72, 3
	v_lshl_add_u32 v220, v57, 1, v51
	v_lshl_add_u64 v[192:193], s[90:91], 0, v[58:59]
	v_lshl_add_u64 v[194:195], s[90:91], 0, v[60:61]
	v_mov_b64_e32 v[114:115], v[146:147]
	v_mov_b64_e32 v[116:117], v[148:149]
	v_mov_b64_e32 v[118:119], v[150:151]
	v_mov_b64_e32 v[120:121], v[152:153]
	v_mov_b64_e32 v[122:123], v[154:155]
	v_mov_b64_e32 v[124:125], v[156:157]
	v_mov_b64_e32 v[126:127], v[158:159]
	v_mov_b32_e32 v48, 0
	v_mov_b32_e32 v49, v187
	v_mov_b32_e32 v50, v187
	v_mov_b32_e32 v51, v187
	v_mov_b32_e32 v52, v187
	v_mov_b32_e32 v53, v187
	v_mov_b32_e32 v54, v187
	v_mov_b32_e32 v55, v187
	v_mov_b32_e32 v56, v187
	v_mov_b32_e32 v57, v187
	v_mov_b32_e32 v58, v187
	v_mov_b32_e32 v59, v187
	v_mov_b32_e32 v60, v187
	v_mov_b32_e32 v61, v187
	v_mov_b32_e32 v62, v187
	v_mov_b32_e32 v63, v187
	v_mov_b32_e32 v64, 0
	v_mov_b32_e32 v65, v187
	v_mov_b32_e32 v66, v187
	v_mov_b32_e32 v67, v187
	v_mov_b32_e32 v68, v187
	v_mov_b32_e32 v69, v187
	v_mov_b32_e32 v70, v187
	v_mov_b32_e32 v71, v187
	v_mov_b32_e32 v72, v187
	v_mov_b32_e32 v73, v187
	v_mov_b32_e32 v74, v187
	v_mov_b32_e32 v75, v187
	v_mov_b32_e32 v76, v187
	v_mov_b32_e32 v77, v187
	v_mov_b32_e32 v78, v187
	v_mov_b32_e32 v79, v187
	v_mov_b32_e32 v80, 0
	v_mov_b32_e32 v81, v187
	v_mov_b32_e32 v82, v187
	v_mov_b32_e32 v83, v187
	v_mov_b32_e32 v84, v187
	v_mov_b32_e32 v85, v187
	v_mov_b32_e32 v86, v187
	v_mov_b32_e32 v87, v187
	v_mov_b32_e32 v88, v187
	v_mov_b32_e32 v89, v187
	v_mov_b32_e32 v90, v187
	v_mov_b32_e32 v91, v187
	v_mov_b32_e32 v92, v187
	v_mov_b32_e32 v93, v187
	v_mov_b32_e32 v94, v187
	v_mov_b32_e32 v95, v187
	v_lshlrev_b32_e32 v201, 4, v196
	v_add_u32_e32 v201, 0xe000, v201
	ds_write_b128 v201, v[0:3]
	ds_write_b128 v201, v[4:7] offset:8192
	ds_write_b128 v201, v[8:11] offset:16384
	ds_write_b128 v201, v[12:15] offset:24576
	ds_write_b128 v201, v[16:19] offset:32768
	ds_write_b128 v201, v[20:23] offset:40960
	v_sub_f32_e32 v96, v96, v221
	v_sub_f32_e32 v97, v97, v221
	v_sub_f32_e32 v98, v98, v221
	v_sub_f32_e32 v99, v99, v221
	v_sub_f32_e32 v100, v100, v221
	v_sub_f32_e32 v101, v101, v221
	v_sub_f32_e32 v102, v102, v221
	v_sub_f32_e32 v103, v103, v221
	v_sub_f32_e32 v104, v104, v221
	v_sub_f32_e32 v105, v105, v221
	v_sub_f32_e32 v106, v106, v221
	v_sub_f32_e32 v107, v107, v221
	v_sub_f32_e32 v108, v108, v221
	v_sub_f32_e32 v109, v109, v221
	v_sub_f32_e32 v110, v110, v221
	v_sub_f32_e32 v111, v111, v221
	v_sub_f32_e32 v128, v128, v221
	v_sub_f32_e32 v129, v129, v221
	v_sub_f32_e32 v130, v130, v221
	v_sub_f32_e32 v131, v131, v221
	v_sub_f32_e32 v132, v132, v221
	v_sub_f32_e32 v133, v133, v221
	v_sub_f32_e32 v134, v134, v221
	v_sub_f32_e32 v135, v135, v221
	v_sub_f32_e32 v136, v136, v221
	v_sub_f32_e32 v137, v137, v221
	v_sub_f32_e32 v138, v138, v221
	v_sub_f32_e32 v139, v139, v221
	v_sub_f32_e32 v140, v140, v221
	v_sub_f32_e32 v141, v141, v221
	v_sub_f32_e32 v142, v142, v221
	v_sub_f32_e32 v143, v143, v221
	v_sub_f32_e32 v224, 0, v221
	v_sub_f32_e32 v225, 0, v221
	v_sub_f32_e32 v226, 0, v221
	v_sub_f32_e32 v227, 0, v221
	v_sub_f32_e32 v228, 0, v221
	v_sub_f32_e32 v229, 0, v221
	v_sub_f32_e32 v230, 0, v221
	v_sub_f32_e32 v231, 0, v221
	v_sub_f32_e32 v232, 0, v221
	v_sub_f32_e32 v233, 0, v221
	v_sub_f32_e32 v234, 0, v221
	v_sub_f32_e32 v235, 0, v221
	v_sub_f32_e32 v236, 0, v221
	v_sub_f32_e32 v237, 0, v221
	v_sub_f32_e32 v238, 0, v221
	v_sub_f32_e32 v239, 0, v221
	s_barrier
	s_branch .LBB0_690

; template <bool MLA, int DK, int DV>
; __device__ __forceinline__ void attn_core(const Params& p, int b, int h, int map, int q0, int nt, char* smem,
;                                           f32x16 (&o)[DV / 32], float& lout) {
;     ...
;     if (has1) {
; #pragma unroll
;       for (int sub = 0; sub < 2; ++sub)
; #pragma unroll
;         for (int i = 0; i < 16; ++i) nxt_[sub][i] = 0.f;
;       constexpr int NM = 2 * NKS;
;       bf16x8 kf[NM];
; #pragma unroll
;       for (int j = 0; j < NM; ++j) kf[j] = *(const bf16x8*)(Kn + ((j / NKS) * 32 + r) * KS_STRIDE + (j % NKS) * 16 + h2 * 8);
; #pragma unroll
;       for (int j = 0; j < NM; ++j) {
;         nxt_[j / NKS] = MFMA32(kf[j], qf[j % NKS], nxt_[j / NKS]);
; #pragma unroll
;         for (int e_ = j * 32 / NM; e_ < (j + 1) * 32 / NM; ++e_) {
;           const float x_ = __builtin_amdgcn_exp2f(fmaf(cur_[e_ >> 4][e_ & 15], sc, -mrun));
;           cur_[e_ >> 4][e_ & 15] = x_; psum += x_;
;         }
;       }
;       __builtin_amdgcn_sched_group_barrier(0x100, NM, 0);
; #pragma unroll
;       for (int j = 0; j < NM; ++j) {
;         __builtin_amdgcn_sched_group_barrier(0x008, 1, 0);
;         __builtin_amdgcn_sched_group_barrier(0x002, 96 / NM, 0);
;       }
;     } else {
; #pragma unroll
;       for (int sub = 0; sub < 2; ++sub)
; #pragma unroll
;         for (int i = 0; i < 16; ++i) { const float x_ = __builtin_amdgcn_exp2f(fmaf(cur_[sub][i], sc, -mrun)); cur_[sub][i] = x_; psum += x_; }
;     }
;     lrun += psum;
;     bf16x8 pb[4];
; #pragma unroll
;     for (int kb = 0; kb < 4; ++kb) {
;       const int sub = kb >> 1, s8 = (kb & 1) * 8;
;       u32x4 pk;
;       pk.x = pack2(cur_[sub][s8 + 0], cur_[sub][s8 + 1]);
;       pk.y = pack2(cur_[sub][s8 + 2], cur_[sub][s8 + 3]);
;       pk.z = pack2(cur_[sub][s8 + 4], cur_[sub][s8 + 5]);
;       pk.w = pack2(cur_[sub][s8 + 6], cur_[sub][s8 + 7]);
;       pb[kb] = __builtin_bit_cast(bf16x8, pk);
;     }
;     float mx = -INFINITY;
; #pragma unroll
;     for (int hb = 0; hb < 2; ++hb) {
;       bf16x8 vf[2][NDVT];
; #pragma unroll
;       for (int q = 0; q < 2; ++q)
; #pragma unroll
;         for (int d = 0; d < NDVT; ++d) {
;           const bft* vp = Vc + (d * 32 + r) * VS_STRIDE + (hb * 2 + q) * 16 + 4 * h2;
;           const u32x2 lo = *(const u32x2*)vp, hi = *(const u32x2*)(vp + 8);
;           const u32x4 pa4 = {lo.x, lo.y, hi.x, hi.y};
.LBB0_692:
	s_or_b64 exec, exec, s[12:13]
	s_add_i32 s12, s72, -2
	s_cmp_lt_u32 s12, s34
	s_cselect_b64 s[70:71], -1, 0
	s_cmp_ge_u32 s12, s34
	s_mov_b64 s[12:13], -1
	s_cbranch_scc1 .Ld2a_cold
	s_and_saveexec_b64 s[12:13], s[8:9]
	s_cbranch_execz .Ld2a_v0
	v_lshl_add_u64 v[198:199], v[192:193], 0, s[64:65]
	v_add_co_u32_e32 v198, vcc, 0x2ec00000, v198
	s_nop 1
	v_addc_co_u32_e32 v199, vcc, 0, v199, vcc
	global_load_dwordx4 v[178:181], v[198:199], off offset:128
.Ld2a_v0:
	s_or_b64 exec, exec, s[12:13]
	s_and_saveexec_b64 s[12:13], s[10:11]
	s_cbranch_execz .Ld2a_v1
	v_lshl_add_u64 v[198:199], v[194:195], 0, s[64:65]
	v_add_co_u32_e32 v198, vcc, 0x2ec00000, v198
	s_nop 1
	v_addc_co_u32_e32 v199, vcc, 0, v199, vcc
	global_load_dwordx4 v[182:185], v[198:199], off offset:128
.Ld2a_v1:
	s_or_b64 exec, exec, s[12:13]
	s_mov_b64 s[12:13], 0
	ds_read_b128 v[0:3], v218 offset:13312
	ds_read_b128 v[4:7], v218 offset:13344
	ds_read_b128 v[8:11], v218 offset:13376
	ds_read_b128 v[12:15], v218 offset:19968
	ds_read_b128 v[16:19], v218 offset:20000
	ds_read_b128 v[20:23], v218 offset:20032
	v_add_u32_e32 v201, 0x6800, v219
	v_add_u32_e32 v189, 0x7800, v219
	v_add_u32_e32 v210, 0x8800, v219
	v_exp_f32_e32 v96, v96
	v_exp_f32_e32 v97, v97
	v_exp_f32_e32 v98, v98
	v_exp_f32_e32 v99, v99
	v_add_f32_e32 v222, v96, v98
	v_add_f32_e32 v223, v97, v99
	s_waitcnt lgkmcnt(5)
	v_mfma_f32_32x32x16_bf16 v[112:127], v[0:3], v[162:165], v[224:239]
	v_exp_f32_e32 v100, v100
	v_exp_f32_e32 v101, v101
	v_exp_f32_e32 v102, v102
	s_waitcnt lgkmcnt(4)
	v_mfma_f32_32x32x16_bf16 v[112:127], v[4:7], v[166:169], v[112:127]
	v_exp_f32_e32 v103, v103
	v_add_f32_e32 v222, v100, v222
	v_add_f32_e32 v223, v101, v223
	v_add_f32_e32 v222, v102, v222
	s_waitcnt lgkmcnt(3)
	v_mfma_f32_32x32x16_bf16 v[112:127], v[8:11], v[170:173], v[112:127]
	ds_read2_b64 v[0:3], v201 offset0:0 offset1:2
	ds_read2_b64 v[4:7], v189 offset0:32 offset1:34
	ds_read2_b64 v[8:11], v210 offset0:64 offset1:66
	v_add_f32_e32 v223, v103, v223
	v_cvt_pk_bf16_f32 v240, v96, v97
	v_cvt_pk_bf16_f32 v241, v98, v99
	v_cvt_pk_bf16_f32 v242, v100, v101
	v_cvt_pk_bf16_f32 v243, v102, v103
	v_exp_f32_e32 v104, v104
	s_waitcnt lgkmcnt(5)
	v_mfma_f32_32x32x16_bf16 v[144:159], v[12:15], v[162:165], v[224:239]
	ds_read2_b64 v[12:15], v201 offset0:4 offset1:6
	v_exp_f32_e32 v105, v105
	v_exp_f32_e32 v106, v106
	s_waitcnt lgkmcnt(5)
	v_mfma_f32_32x32x16_bf16 v[144:159], v[16:19], v[166:169], v[144:159]
	ds_read2_b64 v[16:19], v189 offset0:36 offset1:38
	v_exp_f32_e32 v107, v107
	v_add_f32_e32 v222, v104, v222
	v_add_f32_e32 v223, v105, v223
	v_add_f32_e32 v222, v106, v222
	v_add_f32_e32 v223, v107, v223
	s_waitcnt lgkmcnt(5)
	v_mfma_f32_32x32x16_bf16 v[144:159], v[20:23], v[170:173], v[144:159]
	ds_read2_b64 v[20:23], v210 offset0:68 offset1:70
	v_exp_f32_e32 v108, v108
	v_exp_f32_e32 v109, v109
	v_exp_f32_e32 v110, v110
	s_waitcnt lgkmcnt(5)
	v_mfma_f32_32x32x16_bf16 v[80:95], v[0:3], v[240:243], v[80:95]
	ds_read2_b64 v[0:3], v201 offset0:8 offset1:10
	v_exp_f32_e32 v111, v111
	v_add_f32_e32 v222, v108, v222
	v_add_f32_e32 v223, v109, v223
	v_add_f32_e32 v222, v110, v222
	s_waitcnt lgkmcnt(5)
	v_mfma_f32_32x32x16_bf16 v[64:79], v[4:7], v[240:243], v[64:79]
	ds_read2_b64 v[4:7], v189 offset0:40 offset1:42
	v_add_f32_e32 v223, v111, v223
	v_cvt_pk_bf16_f32 v244, v104, v105
	v_cvt_pk_bf16_f32 v245, v106, v107
	v_cvt_pk_bf16_f32 v246, v108, v109
	v_cvt_pk_bf16_f32 v247, v110, v111
	s_waitcnt lgkmcnt(5)
	v_mfma_f32_32x32x16_bf16 v[48:63], v[8:11], v[240:243], v[48:63]
	ds_read2_b64 v[8:11], v210 offset0:72 offset1:74
	v_exp_f32_e32 v128, v128
	v_exp_f32_e32 v129, v129
	v_exp_f32_e32 v130, v130
	s_waitcnt lgkmcnt(5)
	v_mfma_f32_32x32x16_bf16 v[80:95], v[12:15], v[244:247], v[80:95]
	ds_read2_b64 v[12:15], v201 offset0:12 offset1:14
	v_exp_f32_e32 v131, v131
	v_add_f32_e32 v222, v128, v222
	v_add_f32_e32 v223, v129, v223
	v_add_f32_e32 v222, v130, v222
	s_waitcnt lgkmcnt(5)
	v_mfma_f32_32x32x16_bf16 v[64:79], v[16:19], v[244:247], v[64:79]
	ds_read2_b64 v[16:19], v189 offset0:44 offset1:46
	v_add_f32_e32 v223, v131, v223
	v_exp_f32_e32 v132, v132
	v_exp_f32_e32 v133, v133
	s_waitcnt lgkmcnt(5)
	v_mfma_f32_32x32x16_bf16 v[48:63], v[20:23], v[244:247], v[48:63]
	ds_read2_b64 v[20:23], v210 offset0:76 offset1:78
	v_exp_f32_e32 v134, v134
	v_exp_f32_e32 v135, v135
	v_add_f32_e32 v222, v132, v222
	v_add_f32_e32 v223, v133, v223
	v_add_f32_e32 v222, v134, v222
	v_add_f32_e32 v223, v135, v223
	v_cvt_pk_bf16_f32 v248, v128, v129
	v_cvt_pk_bf16_f32 v249, v130, v131
	v_cvt_pk_bf16_f32 v250, v132, v133
	v_cvt_pk_bf16_f32 v251, v134, v135
	s_waitcnt lgkmcnt(5)
	s_nop 0
	v_mfma_f32_32x32x16_bf16 v[80:95], v[0:3], v[248:251], v[80:95]
	s_waitcnt lgkmcnt(4)
	v_mfma_f32_32x32x16_bf16 v[64:79], v[4:7], v[248:251], v[64:79]
	v_exp_f32_e32 v136, v136
	v_exp_f32_e32 v137, v137
	v_exp_f32_e32 v138, v138
	s_waitcnt lgkmcnt(3)
	v_mfma_f32_32x32x16_bf16 v[48:63], v[8:11], v[248:251], v[48:63]
	v_exp_f32_e32 v139, v139
	v_add_f32_e32 v222, v136, v222
	v_add_f32_e32 v223, v137, v223
	v_add_f32_e32 v222, v138, v222
	v_add_f32_e32 v223, v139, v223
	v_exp_f32_e32 v140, v140
	v_exp_f32_e32 v141, v141
	v_exp_f32_e32 v142, v142
	v_exp_f32_e32 v143, v143
	v_add_f32_e32 v222, v140, v222
	v_add_f32_e32 v223, v141, v223
	v_add_f32_e32 v222, v142, v222
	v_add_f32_e32 v223, v143, v223
	v_cvt_pk_bf16_f32 v202, v136, v137
	v_cvt_pk_bf16_f32 v203, v138, v139
	v_cvt_pk_bf16_f32 v204, v140, v141
	v_cvt_pk_bf16_f32 v205, v142, v143
	s_waitcnt lgkmcnt(2)
	s_nop 0
	v_mfma_f32_32x32x16_bf16 v[80:95], v[12:15], v[202:205], v[80:95]
	s_waitcnt lgkmcnt(1)
	v_mfma_f32_32x32x16_bf16 v[64:79], v[16:19], v[202:205], v[64:79]
	s_waitcnt lgkmcnt(0)
	v_mfma_f32_32x32x16_bf16 v[48:63], v[20:23], v[202:205], v[48:63]
	v_add_f32_e32 v222, v222, v223
	v_add_f32_e32 v187, v187, v222
	v_cmp_lt_f32_e32 vcc, 0x45800000, v222
	s_cbranch_vccz .LBB0_703
; template <bool MLA, int DK, int DV>
; __device__ __forceinline__ void attn_core(const Params& p, int b, int h, int map, int q0, int nt, char* smem,
;                                           f32x16 (&o)[DV / 32], float& lout) {
;     ...
;     if (has1) {
;       mx *= sc;
;       if (__any(mx > mrun + 12.f)) {
;         mx = fmaxf(mx, __shfl_xor(mx, 32));
;         const float mnew = fmaxf(mrun, mx);
;         const float alpha = __builtin_amdgcn_exp2f(mrun - mnew);
;         mrun = mnew;
;         lrun *= alpha;
; #pragma unroll
;         for (int d = 0; d < NDVT; ++d)
; #pragma unroll
;           for (int i = 0; i < 16; ++i) o[d][i] *= alpha;
;       }
;     }
	v_max3_f32 v222, v96, v97, v98
	v_max3_f32 v222, v222, v99, v100
	v_max3_f32 v222, v222, v101, v102
	v_max3_f32 v222, v222, v103, v104
	v_max3_f32 v222, v222, v105, v106
	v_max3_f32 v222, v222, v107, v108
	v_max3_f32 v222, v222, v109, v110
	v_max3_f32 v222, v222, v111, v128
	v_max3_f32 v222, v222, v129, v130
	v_max3_f32 v222, v222, v131, v132
	v_max3_f32 v222, v222, v133, v134
	v_max3_f32 v222, v222, v135, v136
	v_max3_f32 v222, v222, v137, v138
	v_max3_f32 v222, v222, v139, v140
	v_max3_f32 v222, v222, v141, v142
	v_max_f32_e32 v222, v222, v143
	ds_bpermute_b32 v223, v215, v222
	s_waitcnt lgkmcnt(0)
	v_max_f32_e32 v222, v222, v223
	v_frexp_exp_i32_f32_e32 v223, v222
	v_max_i32_e32 v223, 0, v223
	v_sub_u32_e32 v252, 0, v223
	v_ldexp_f32 v252, 1.0, v252
	v_cvt_f32_i32_e32 v223, v223
	v_mul_f32_e32 v187, v187, v252
	v_mul_f32_e32 v80, v80, v252
	v_mul_f32_e32 v81, v81, v252
	v_mul_f32_e32 v82, v82, v252
	v_mul_f32_e32 v83, v83, v252
	v_mul_f32_e32 v84, v84, v252
	v_mul_f32_e32 v85, v85, v252
	v_mul_f32_e32 v86, v86, v252
	v_mul_f32_e32 v87, v87, v252
	v_mul_f32_e32 v88, v88, v252
	v_mul_f32_e32 v89, v89, v252
	v_mul_f32_e32 v90, v90, v252
	v_mul_f32_e32 v91, v91, v252
	v_mul_f32_e32 v92, v92, v252
	v_mul_f32_e32 v93, v93, v252
	v_mul_f32_e32 v94, v94, v252
	v_mul_f32_e32 v95, v95, v252
	v_mul_f32_e32 v64, v64, v252
	v_mul_f32_e32 v65, v65, v252
	v_mul_f32_e32 v66, v66, v252
	v_mul_f32_e32 v67, v67, v252
	v_mul_f32_e32 v68, v68, v252
	v_mul_f32_e32 v69, v69, v252
	v_mul_f32_e32 v70, v70, v252
	v_mul_f32_e32 v71, v71, v252
	v_mul_f32_e32 v72, v72, v252
	v_mul_f32_e32 v73, v73, v252
	v_mul_f32_e32 v74, v74, v252
	v_mul_f32_e32 v75, v75, v252
	v_mul_f32_e32 v76, v76, v252
	v_mul_f32_e32 v77, v77, v252
	v_mul_f32_e32 v78, v78, v252
	v_mul_f32_e32 v79, v79, v252
	v_mul_f32_e32 v48, v48, v252
	v_mul_f32_e32 v49, v49, v252
	v_mul_f32_e32 v50, v50, v252
	v_mul_f32_e32 v51, v51, v252
	v_mul_f32_e32 v52, v52, v252
	v_mul_f32_e32 v53, v53, v252
	v_mul_f32_e32 v54, v54, v252
	v_mul_f32_e32 v55, v55, v252
	v_mul_f32_e32 v56, v56, v252
	v_mul_f32_e32 v57, v57, v252
	v_mul_f32_e32 v58, v58, v252
	v_mul_f32_e32 v59, v59, v252
	v_mul_f32_e32 v60, v60, v252
	v_mul_f32_e32 v61, v61, v252
	v_mul_f32_e32 v62, v62, v252
	v_mul_f32_e32 v63, v63, v252
	v_sub_f32_e32 v224, v224, v223
	v_sub_f32_e32 v225, v225, v223
	v_sub_f32_e32 v226, v226, v223
	v_sub_f32_e32 v227, v227, v223
	v_sub_f32_e32 v228, v228, v223
	v_sub_f32_e32 v229, v229, v223
	v_sub_f32_e32 v230, v230, v223
	v_sub_f32_e32 v231, v231, v223
	v_sub_f32_e32 v232, v232, v223
	v_sub_f32_e32 v233, v233, v223
	v_sub_f32_e32 v234, v234, v223
	v_sub_f32_e32 v235, v235, v223
	v_sub_f32_e32 v236, v236, v223
	v_sub_f32_e32 v237, v237, v223
	v_sub_f32_e32 v238, v238, v223
	v_sub_f32_e32 v239, v239, v223
	v_sub_f32_e32 v112, v112, v223
	v_sub_f32_e32 v113, v113, v223
	v_sub_f32_e32 v114, v114, v223
	v_sub_f32_e32 v115, v115, v223
	v_sub_f32_e32 v116, v116, v223
	v_sub_f32_e32 v117, v117, v223
	v_sub_f32_e32 v118, v118, v223
	v_sub_f32_e32 v119, v119, v223
	v_sub_f32_e32 v120, v120, v223
	v_sub_f32_e32 v121, v121, v223
	v_sub_f32_e32 v122, v122, v223
	v_sub_f32_e32 v123, v123, v223
	v_sub_f32_e32 v124, v124, v223
	v_sub_f32_e32 v125, v125, v223
	v_sub_f32_e32 v126, v126, v223
	v_sub_f32_e32 v127, v127, v223
	v_sub_f32_e32 v144, v144, v223
	v_sub_f32_e32 v145, v145, v223
	v_sub_f32_e32 v146, v146, v223
	v_sub_f32_e32 v147, v147, v223
	v_sub_f32_e32 v148, v148, v223
	v_sub_f32_e32 v149, v149, v223
	v_sub_f32_e32 v150, v150, v223
	v_sub_f32_e32 v151, v151, v223
	v_sub_f32_e32 v152, v152, v223
	v_sub_f32_e32 v153, v153, v223
	v_sub_f32_e32 v154, v154, v223
	v_sub_f32_e32 v155, v155, v223
	v_sub_f32_e32 v156, v156, v223
	v_sub_f32_e32 v157, v157, v223
	v_sub_f32_e32 v158, v158, v223
	v_sub_f32_e32 v159, v159, v223
	v_add_f32_e32 v221, v221, v223
	s_branch .LBB0_703
; DI unsigned pack2(float lo, float hi) { f2v_ f = {lo, hi}; b2v_ b = __builtin_convertvector(f, b2v_); return __builtin_bit_cast(unsigned, b); }
; #define MFMA32(a, b, c) __builtin_amdgcn_mfma_f32_32x32x16_bf16((a), (b), (c), 0, 0, 0)
; template <bool MLA, int DK, int DV>
; __device__ __forceinline__ void attn_core(const Params& p, int b, int h, int map, int q0, int nt, char* smem,
;                                           f32x16 (&o)[DV / 32], float& lout) {
;     ...
;     } else {
; #pragma unroll
;       for (int sub = 0; sub < 2; ++sub)
; #pragma unroll
;         for (int i = 0; i < 16; ++i) { const float x_ = __builtin_amdgcn_exp2f(fmaf(cur_[sub][i], sc, -mrun)); cur_[sub][i] = x_; psum += x_; }
;     }
;     lrun += psum;
;     bf16x8 pb[4];
; #pragma unroll
;     for (int kb = 0; kb < 4; ++kb) {
;       const int sub = kb >> 1, s8 = (kb & 1) * 8;
;       u32x4 pk;
;       pk.x = pack2(cur_[sub][s8 + 0], cur_[sub][s8 + 1]);
;       pk.y = pack2(cur_[sub][s8 + 2], cur_[sub][s8 + 3]);
;       pk.z = pack2(cur_[sub][s8 + 4], cur_[sub][s8 + 5]);
;       pk.w = pack2(cur_[sub][s8 + 6], cur_[sub][s8 + 7]);
;       pb[kb] = __builtin_bit_cast(bf16x8, pk);
;     }
;     float mx = -INFINITY;
; #pragma unroll
;     for (int hb = 0; hb < 2; ++hb) {
;       bf16x8 vf[2][NDVT];
; #pragma unroll
;       for (int q = 0; q < 2; ++q)
; #pragma unroll
;         for (int d = 0; d < NDVT; ++d) {
;           const bft* vp = Vc + (d * 32 + r) * VS_STRIDE + (hb * 2 + q) * 16 + 4 * h2;
;           const u32x2 lo = *(const u32x2*)vp, hi = *(const u32x2*)(vp + 8);
;           const u32x4 pa4 = {lo.x, lo.y, hi.x, hi.y};
;           vf[q][d] = __builtin_bit_cast(bf16x8, pa4);
;         }
; #pragma unroll
;       for (int q = 0; q < 2; ++q) {
;         const int kb = hb * 2 + q;
; #pragma unroll
;         for (int d = 0; d < NDVT; ++d) o[d] = MFMA32(vf[q][d], pb[kb], o[d]);
; #pragma unroll
;         for (int i = 0; i < 8; ++i) mx = fmaxf(mx, nxt_[kb >> 1][(kb & 1) * 8 + i]);
;       }
;     }
.Ld2a_cold:
	v_mov_b32_e32 v210, v96
	v_mov_b32_e32 v252, v97
	v_mov_b32_e32 v251, v98
	v_mov_b32_e32 v250, v99
	v_mov_b32_e32 v249, v100
	v_mov_b32_e32 v248, v101
	v_mov_b32_e32 v247, v102
	v_mov_b32_e32 v245, v103
	v_mov_b32_e32 v244, v104
	v_mov_b32_e32 v243, v105
	v_mov_b32_e32 v242, v106
	v_mov_b32_e32 v241, v107
	v_mov_b32_e32 v240, v108
	v_mov_b32_e32 v239, v109
	v_mov_b32_e32 v238, v110
	v_mov_b32_e32 v237, v111
	v_mov_b32_e32 v236, v128
	v_mov_b32_e32 v235, v129
	v_mov_b32_e32 v234, v130
	v_mov_b32_e32 v233, v131
	v_mov_b32_e32 v232, v132
	v_mov_b32_e32 v231, v133
	v_mov_b32_e32 v230, v134
	v_mov_b32_e32 v229, v135
	v_mov_b32_e32 v228, v136
	v_mov_b32_e32 v227, v137
	v_mov_b32_e32 v189, v138
	v_mov_b32_e32 v222, v139
	v_mov_b32_e32 v223, v140
	v_mov_b32_e32 v224, v141
	v_mov_b32_e32 v225, v142
	v_mov_b32_e32 v226, v143
	v_exp_f32_e32 v96, v210
	v_exp_f32_e32 v97, v252
	v_exp_f32_e32 v98, v251
	v_exp_f32_e32 v99, v250
	v_add_f32_e32 v100, 0, v96
	v_add_f32_e32 v100, v97, v100
	v_add_f32_e32 v100, v98, v100
	v_add_f32_e32 v104, v99, v100
	v_exp_f32_e32 v100, v249
	v_exp_f32_e32 v101, v248
	v_exp_f32_e32 v102, v247
	v_exp_f32_e32 v103, v245
	v_add_f32_e32 v104, v100, v104
	v_add_f32_e32 v104, v101, v104
	v_add_f32_e32 v104, v102, v104
	v_add_f32_e32 v108, v103, v104
	v_exp_f32_e32 v104, v244
	v_exp_f32_e32 v105, v243
	v_exp_f32_e32 v106, v242
	v_exp_f32_e32 v107, v241
	v_add_f32_e32 v108, v104, v108
	v_add_f32_e32 v108, v105, v108
	v_add_f32_e32 v108, v106, v108
	v_add_f32_e32 v128, v107, v108
	v_exp_f32_e32 v108, v240
	v_exp_f32_e32 v109, v239
	v_exp_f32_e32 v110, v238
	v_exp_f32_e32 v111, v237
	v_add_f32_e32 v128, v108, v128
	v_add_f32_e32 v128, v109, v128
	v_add_f32_e32 v128, v110, v128
	v_add_f32_e32 v132, v111, v128
	v_exp_f32_e32 v128, v236
	v_exp_f32_e32 v129, v235
	v_exp_f32_e32 v130, v234
	v_exp_f32_e32 v131, v233
	v_add_f32_e32 v132, v128, v132
	v_add_f32_e32 v132, v129, v132
	v_add_f32_e32 v132, v130, v132
	v_add_f32_e32 v136, v131, v132
	v_exp_f32_e32 v132, v232
	v_exp_f32_e32 v133, v231
	v_exp_f32_e32 v134, v230
	v_exp_f32_e32 v135, v229
	v_add_f32_e32 v136, v132, v136
	v_add_f32_e32 v136, v133, v136
	v_add_f32_e32 v136, v134, v136
	v_add_f32_e32 v140, v135, v136
	v_exp_f32_e32 v136, v228
	v_exp_f32_e32 v137, v227
	v_exp_f32_e32 v138, v189
	v_exp_f32_e32 v139, v222
	v_add_f32_e32 v140, v136, v140
	v_add_f32_e32 v140, v137, v140
	v_add_f32_e32 v140, v138, v140
	v_add_f32_e32 v198, v139, v140
	v_exp_f32_e32 v140, v223
	v_exp_f32_e32 v141, v224
	v_exp_f32_e32 v142, v225
	v_exp_f32_e32 v143, v226
	v_add_f32_e32 v198, v140, v198
	v_add_f32_e32 v198, v141, v198
	v_add_f32_e32 v198, v142, v198
	v_add_f32_e32 v246, v143, v198
	s_mov_b64 s[12:13], 0
.LBB0_700:
	v_add_u32_e32 v189, 0x6800, v219
	ds_read2_b64 v[222:225], v189 offset1:2
	v_cvt_pk_bf16_f32 v226, v96, v97
	v_cvt_pk_bf16_f32 v227, v98, v99
	v_cvt_pk_bf16_f32 v228, v100, v101
	v_cvt_pk_bf16_f32 v229, v102, v103
	v_add_u32_e32 v198, 0x7800, v219
	v_add_u32_e32 v199, 0x8800, v219
	v_add_f32_e32 v187, v187, v246
	s_andn2_b64 vcc, exec, s[70:71]
	s_waitcnt lgkmcnt(0)
	v_mfma_f32_32x32x16_bf16 v[80:95], v[222:225], v[226:229], v[80:95]
	ds_read2_b64 v[222:225], v198 offset0:32 offset1:34
	s_waitcnt lgkmcnt(0)
	v_mfma_f32_32x32x16_bf16 v[64:79], v[222:225], v[226:229], v[64:79]
	ds_read2_b64 v[222:225], v199 offset0:64 offset1:66
	s_waitcnt lgkmcnt(0)
	v_mfma_f32_32x32x16_bf16 v[48:63], v[222:225], v[226:229], v[48:63]
	ds_read2_b64 v[222:225], v189 offset0:4 offset1:6
	v_cvt_pk_bf16_f32 v226, v104, v105
	v_cvt_pk_bf16_f32 v227, v106, v107
	v_cvt_pk_bf16_f32 v228, v108, v109
	v_cvt_pk_bf16_f32 v229, v110, v111
	s_waitcnt lgkmcnt(0)
	s_nop 0
	v_mfma_f32_32x32x16_bf16 v[80:95], v[222:225], v[226:229], v[80:95]
	ds_read2_b64 v[222:225], v198 offset0:36 offset1:38
	s_waitcnt lgkmcnt(0)
	v_mfma_f32_32x32x16_bf16 v[64:79], v[222:225], v[226:229], v[64:79]
	ds_read2_b64 v[222:225], v199 offset0:68 offset1:70
	s_waitcnt lgkmcnt(0)
	v_mfma_f32_32x32x16_bf16 v[48:63], v[222:225], v[226:229], v[48:63]
	ds_read2_b64 v[222:225], v189 offset0:8 offset1:10
	v_cvt_pk_bf16_f32 v226, v128, v129
	v_cvt_pk_bf16_f32 v227, v130, v131
	v_cvt_pk_bf16_f32 v228, v132, v133
	v_cvt_pk_bf16_f32 v229, v134, v135
	s_waitcnt lgkmcnt(0)
	s_nop 0
	v_mfma_f32_32x32x16_bf16 v[80:95], v[222:225], v[226:229], v[80:95]
	ds_read2_b64 v[222:225], v198 offset0:40 offset1:42
	s_waitcnt lgkmcnt(0)
	v_mfma_f32_32x32x16_bf16 v[64:79], v[222:225], v[226:229], v[64:79]
	ds_read2_b64 v[222:225], v199 offset0:72 offset1:74
	s_waitcnt lgkmcnt(0)
	v_mfma_f32_32x32x16_bf16 v[48:63], v[222:225], v[226:229], v[48:63]
	ds_read2_b64 v[222:225], v189 offset0:12 offset1:14
	v_cvt_pk_bf16_f32 v226, v136, v137
	v_cvt_pk_bf16_f32 v227, v138, v139
	v_cvt_pk_bf16_f32 v228, v140, v141
	v_cvt_pk_bf16_f32 v229, v142, v143
	v_cndmask_b32_e64 v189, 0, 1, s[70:71]
	v_cmp_ne_u32_e64 s[12:13], 1, v189
	s_waitcnt lgkmcnt(0)
	v_mfma_f32_32x32x16_bf16 v[80:95], v[222:225], v[226:229], v[80:95]
	ds_read2_b64 v[222:225], v198 offset0:44 offset1:46
	s_waitcnt lgkmcnt(0)
	v_mfma_f32_32x32x16_bf16 v[64:79], v[222:225], v[226:229], v[64:79]
	ds_read2_b64 v[222:225], v199 offset0:76 offset1:78
	s_waitcnt lgkmcnt(0)
	v_mfma_f32_32x32x16_bf16 v[48:63], v[222:225], v[226:229], v[48:63]
	s_branch .LBB0_703

; template <bool MLA, int DK, int DV>
; __device__ __forceinline__ void attn_core(const Params& p, int b, int h, int map, int q0, int nt, char* smem,
;                                           f32x16 (&o)[DV / 32], float& lout) {
;     ...
;     if (has1) {
; #pragma unroll
;       for (int sub = 0; sub < 2; ++sub)
; #pragma unroll
;         for (int i = 0; i < 16; ++i) nxt_[sub][i] = 0.f;
;       constexpr int NM = 2 * NKS;
;       bf16x8 kf[NM];
; #pragma unroll
;       for (int j = 0; j < NM; ++j) kf[j] = *(const bf16x8*)(Kn + ((j / NKS) * 32 + r) * KS_STRIDE + (j % NKS) * 16 + h2 * 8);
; #pragma unroll
;       for (int j = 0; j < NM; ++j) {
;         nxt_[j / NKS] = MFMA32(kf[j], qf[j % NKS], nxt_[j / NKS]);
; #pragma unroll
;         for (int e_ = j * 32 / NM; e_ < (j + 1) * 32 / NM; ++e_) {
;           const float x_ = __builtin_amdgcn_exp2f(fmaf(cur_[e_ >> 4][e_ & 15], sc, -mrun));
;           cur_[e_ >> 4][e_ & 15] = x_; psum += x_;
;         }
;       }
;       __builtin_amdgcn_sched_group_barrier(0x100, NM, 0);
; #pragma unroll
;       for (int j = 0; j < NM; ++j) {
;         __builtin_amdgcn_sched_group_barrier(0x008, 1, 0);
;         __builtin_amdgcn_sched_group_barrier(0x002, 96 / NM, 0);
;       }
;     } else {
; #pragma unroll
;       for (int sub = 0; sub < 2; ++sub)
; #pragma unroll
;         for (int i = 0; i < 16; ++i) { const float x_ = __builtin_amdgcn_exp2f(fmaf(cur_[sub][i], sc, -mrun)); cur_[sub][i] = x_; psum += x_; }
;     }
;     lrun += psum;
;     bf16x8 pb[4];
; #pragma unroll
;     for (int kb = 0; kb < 4; ++kb) {
;       const int sub = kb >> 1, s8 = (kb & 1) * 8;
;       u32x4 pk;
;       pk.x = pack2(cur_[sub][s8 + 0], cur_[sub][s8 + 1]);
;       pk.y = pack2(cur_[sub][s8 + 2], cur_[sub][s8 + 3]);
;       pk.z = pack2(cur_[sub][s8 + 4], cur_[sub][s8 + 5]);
;       pk.w = pack2(cur_[sub][s8 + 6], cur_[sub][s8 + 7]);
;       pb[kb] = __builtin_bit_cast(bf16x8, pk);
;     }
;     float mx = -INFINITY;
; #pragma unroll
;     for (int hb = 0; hb < 2; ++hb) {
;       bf16x8 vf[2][NDVT];
; #pragma unroll
;       for (int q = 0; q < 2; ++q)
; #pragma unroll
;         for (int d = 0; d < NDVT; ++d) {
;           const bft* vp = Vc + (d * 32 + r) * VS_STRIDE + (hb * 2 + q) * 16 + 4 * h2;
;           const u32x2 lo = *(const u32x2*)vp, hi = *(const u32x2*)(vp + 8);
;           const u32x4 pa4 = {lo.x, lo.y, hi.x, hi.y};
.LBB0_713:
	s_or_b64 exec, exec, s[12:13]
	s_and_b64 vcc, exec, s[16:17]
	s_cbranch_vccnz .Ld2b_cold
	s_and_saveexec_b64 s[12:13], s[8:9]
	s_cbranch_execz .Ld2b_v0
	v_lshl_add_u64 v[198:199], v[192:193], 0, s[64:65]
	v_add_co_u32_e32 v198, vcc, 0x2ec00000, v198
	s_nop 1
	v_addc_co_u32_e32 v199, vcc, 0, v199, vcc
	global_load_dwordx4 v[178:181], v[198:199], off offset:256
.Ld2b_v0:
	s_or_b64 exec, exec, s[12:13]
	s_and_saveexec_b64 s[12:13], s[10:11]
	s_cbranch_execz .Ld2b_v1
	v_lshl_add_u64 v[198:199], v[194:195], 0, s[64:65]
	v_add_co_u32_e32 v198, vcc, 0x2ec00000, v198
	s_nop 1
	v_addc_co_u32_e32 v199, vcc, 0, v199, vcc
	global_load_dwordx4 v[182:185], v[198:199], off offset:256
.Ld2b_v1:
	s_or_b64 exec, exec, s[12:13]
	s_mov_b64 s[12:13], 0
	ds_read_b128 v[0:3], v218 offset:0
	ds_read_b128 v[4:7], v218 offset:32
	ds_read_b128 v[8:11], v218 offset:64
	ds_read_b128 v[12:15], v218 offset:6656
	ds_read_b128 v[16:19], v218 offset:6688
	ds_read_b128 v[20:23], v218 offset:6720
	v_add_u32_e32 v201, 0x9800, v219
	v_add_u32_e32 v189, 0xa800, v219
	v_add_u32_e32 v210, 0xb800, v219
	v_exp_f32_e32 v112, v112
	v_exp_f32_e32 v113, v113
	v_exp_f32_e32 v114, v114
	v_exp_f32_e32 v115, v115
	v_add_f32_e32 v222, v112, v114
	v_add_f32_e32 v223, v113, v115
	s_waitcnt lgkmcnt(5)
	v_mfma_f32_32x32x16_bf16 v[96:111], v[0:3], v[162:165], v[224:239]
	v_exp_f32_e32 v116, v116
	v_exp_f32_e32 v117, v117
	v_exp_f32_e32 v118, v118
	s_waitcnt lgkmcnt(4)
	v_mfma_f32_32x32x16_bf16 v[96:111], v[4:7], v[166:169], v[96:111]
	v_exp_f32_e32 v119, v119
	v_add_f32_e32 v222, v116, v222
	v_add_f32_e32 v223, v117, v223
	v_add_f32_e32 v222, v118, v222
	s_waitcnt lgkmcnt(3)
	v_mfma_f32_32x32x16_bf16 v[96:111], v[8:11], v[170:173], v[96:111]
	ds_read2_b64 v[0:3], v201 offset0:96 offset1:98
	ds_read2_b64 v[4:7], v189 offset0:128 offset1:130
	ds_read2_b64 v[8:11], v210 offset0:160 offset1:162
	v_add_f32_e32 v223, v119, v223
	v_cvt_pk_bf16_f32 v240, v112, v113
	v_cvt_pk_bf16_f32 v241, v114, v115
	v_cvt_pk_bf16_f32 v242, v116, v117
	v_cvt_pk_bf16_f32 v243, v118, v119
	v_exp_f32_e32 v120, v120
	s_waitcnt lgkmcnt(5)
	v_mfma_f32_32x32x16_bf16 v[128:143], v[12:15], v[162:165], v[224:239]
	ds_read2_b64 v[12:15], v201 offset0:100 offset1:102
	v_exp_f32_e32 v121, v121
	v_exp_f32_e32 v122, v122
	s_waitcnt lgkmcnt(5)
	v_mfma_f32_32x32x16_bf16 v[128:143], v[16:19], v[166:169], v[128:143]
	ds_read2_b64 v[16:19], v189 offset0:132 offset1:134
	v_exp_f32_e32 v123, v123
	v_add_f32_e32 v222, v120, v222
	v_add_f32_e32 v223, v121, v223
	v_add_f32_e32 v222, v122, v222
	v_add_f32_e32 v223, v123, v223
	s_waitcnt lgkmcnt(5)
	v_mfma_f32_32x32x16_bf16 v[128:143], v[20:23], v[170:173], v[128:143]
	ds_read2_b64 v[20:23], v210 offset0:164 offset1:166
	v_exp_f32_e32 v124, v124
	v_exp_f32_e32 v125, v125
	v_exp_f32_e32 v126, v126
	s_waitcnt lgkmcnt(5)
	v_mfma_f32_32x32x16_bf16 v[80:95], v[0:3], v[240:243], v[80:95]
	ds_read2_b64 v[0:3], v201 offset0:104 offset1:106
	v_exp_f32_e32 v127, v127
	v_add_f32_e32 v222, v124, v222
	v_add_f32_e32 v223, v125, v223
	v_add_f32_e32 v222, v126, v222
	s_waitcnt lgkmcnt(5)
	v_mfma_f32_32x32x16_bf16 v[64:79], v[4:7], v[240:243], v[64:79]
	ds_read2_b64 v[4:7], v189 offset0:136 offset1:138
	v_add_f32_e32 v223, v127, v223
	v_cvt_pk_bf16_f32 v244, v120, v121
	v_cvt_pk_bf16_f32 v245, v122, v123
	v_cvt_pk_bf16_f32 v246, v124, v125
	v_cvt_pk_bf16_f32 v247, v126, v127
	s_waitcnt lgkmcnt(5)
	v_mfma_f32_32x32x16_bf16 v[48:63], v[8:11], v[240:243], v[48:63]
	ds_read2_b64 v[8:11], v210 offset0:168 offset1:170
	v_exp_f32_e32 v144, v144
	v_exp_f32_e32 v145, v145
	v_exp_f32_e32 v146, v146
	s_waitcnt lgkmcnt(5)
	v_mfma_f32_32x32x16_bf16 v[80:95], v[12:15], v[244:247], v[80:95]
	ds_read2_b64 v[12:15], v201 offset0:108 offset1:110
	v_exp_f32_e32 v147, v147
	v_add_f32_e32 v222, v144, v222
	v_add_f32_e32 v223, v145, v223
	v_add_f32_e32 v222, v146, v222
	s_waitcnt lgkmcnt(5)
	v_mfma_f32_32x32x16_bf16 v[64:79], v[16:19], v[244:247], v[64:79]
	ds_read2_b64 v[16:19], v189 offset0:140 offset1:142
	v_add_f32_e32 v223, v147, v223
	v_exp_f32_e32 v148, v148
	v_exp_f32_e32 v149, v149
	s_waitcnt lgkmcnt(5)
	v_mfma_f32_32x32x16_bf16 v[48:63], v[20:23], v[244:247], v[48:63]
	ds_read2_b64 v[20:23], v210 offset0:172 offset1:174
	v_exp_f32_e32 v150, v150
	v_exp_f32_e32 v151, v151
	v_add_f32_e32 v222, v148, v222
	v_add_f32_e32 v223, v149, v223
	v_add_f32_e32 v222, v150, v222
	v_add_f32_e32 v223, v151, v223
	v_cvt_pk_bf16_f32 v248, v144, v145
	v_cvt_pk_bf16_f32 v249, v146, v147
	v_cvt_pk_bf16_f32 v250, v148, v149
	v_cvt_pk_bf16_f32 v251, v150, v151
	s_waitcnt lgkmcnt(5)
	s_nop 0
	v_mfma_f32_32x32x16_bf16 v[80:95], v[0:3], v[248:251], v[80:95]
	s_waitcnt lgkmcnt(4)
	v_mfma_f32_32x32x16_bf16 v[64:79], v[4:7], v[248:251], v[64:79]
	v_exp_f32_e32 v152, v152
	v_exp_f32_e32 v153, v153
	v_exp_f32_e32 v154, v154
	s_waitcnt lgkmcnt(3)
	v_mfma_f32_32x32x16_bf16 v[48:63], v[8:11], v[248:251], v[48:63]
	v_exp_f32_e32 v155, v155
	v_add_f32_e32 v222, v152, v222
	v_add_f32_e32 v223, v153, v223
	v_add_f32_e32 v222, v154, v222
	v_add_f32_e32 v223, v155, v223
	v_exp_f32_e32 v156, v156
	v_exp_f32_e32 v157, v157
	v_exp_f32_e32 v158, v158
	v_exp_f32_e32 v159, v159
	v_add_f32_e32 v222, v156, v222
	v_add_f32_e32 v223, v157, v223
	v_add_f32_e32 v222, v158, v222
	v_add_f32_e32 v223, v159, v223
	v_cvt_pk_bf16_f32 v202, v152, v153
	v_cvt_pk_bf16_f32 v203, v154, v155
	v_cvt_pk_bf16_f32 v204, v156, v157
	v_cvt_pk_bf16_f32 v205, v158, v159
	s_waitcnt lgkmcnt(2)
	s_nop 0
	v_mfma_f32_32x32x16_bf16 v[80:95], v[12:15], v[202:205], v[80:95]
	s_waitcnt lgkmcnt(1)
	v_mfma_f32_32x32x16_bf16 v[64:79], v[16:19], v[202:205], v[64:79]
	s_waitcnt lgkmcnt(0)
	v_mfma_f32_32x32x16_bf16 v[48:63], v[20:23], v[202:205], v[48:63]
	v_add_f32_e32 v222, v222, v223
	v_add_f32_e32 v187, v187, v222
	v_cmp_lt_f32_e32 vcc, 0x45800000, v222
	s_cbranch_vccz .LBB0_724
; template <bool MLA, int DK, int DV>
; __device__ __forceinline__ void attn_core(const Params& p, int b, int h, int map, int q0, int nt, char* smem,
;                                           f32x16 (&o)[DV / 32], float& lout) {
;     ...
;     if (has1) {
;       mx *= sc;
;       if (__any(mx > mrun + 12.f)) {
;         mx = fmaxf(mx, __shfl_xor(mx, 32));
;         const float mnew = fmaxf(mrun, mx);
;         const float alpha = __builtin_amdgcn_exp2f(mrun - mnew);
;         mrun = mnew;
;         lrun *= alpha;
; #pragma unroll
;         for (int d = 0; d < NDVT; ++d)
; #pragma unroll
;           for (int i = 0; i < 16; ++i) o[d][i] *= alpha;
;       }
;     }
	v_max3_f32 v222, v112, v113, v114
	v_max3_f32 v222, v222, v115, v116
	v_max3_f32 v222, v222, v117, v118
	v_max3_f32 v222, v222, v119, v120
	v_max3_f32 v222, v222, v121, v122
	v_max3_f32 v222, v222, v123, v124
	v_max3_f32 v222, v222, v125, v126
	v_max3_f32 v222, v222, v127, v144
	v_max3_f32 v222, v222, v145, v146
	v_max3_f32 v222, v222, v147, v148
	v_max3_f32 v222, v222, v149, v150
	v_max3_f32 v222, v222, v151, v152
	v_max3_f32 v222, v222, v153, v154
	v_max3_f32 v222, v222, v155, v156
	v_max3_f32 v222, v222, v157, v158
	v_max_f32_e32 v222, v222, v159
	ds_bpermute_b32 v223, v215, v222
	s_waitcnt lgkmcnt(0)
	v_max_f32_e32 v222, v222, v223
	v_frexp_exp_i32_f32_e32 v223, v222
	v_max_i32_e32 v223, 0, v223
	v_sub_u32_e32 v252, 0, v223
	v_ldexp_f32 v252, 1.0, v252
	v_cvt_f32_i32_e32 v223, v223
	v_mul_f32_e32 v187, v187, v252
	v_mul_f32_e32 v80, v80, v252
	v_mul_f32_e32 v81, v81, v252
	v_mul_f32_e32 v82, v82, v252
	v_mul_f32_e32 v83, v83, v252
	v_mul_f32_e32 v84, v84, v252
	v_mul_f32_e32 v85, v85, v252
	v_mul_f32_e32 v86, v86, v252
	v_mul_f32_e32 v87, v87, v252
	v_mul_f32_e32 v88, v88, v252
	v_mul_f32_e32 v89, v89, v252
	v_mul_f32_e32 v90, v90, v252
	v_mul_f32_e32 v91, v91, v252
	v_mul_f32_e32 v92, v92, v252
	v_mul_f32_e32 v93, v93, v252
	v_mul_f32_e32 v94, v94, v252
	v_mul_f32_e32 v95, v95, v252
	v_mul_f32_e32 v64, v64, v252
	v_mul_f32_e32 v65, v65, v252
	v_mul_f32_e32 v66, v66, v252
	v_mul_f32_e32 v67, v67, v252
	v_mul_f32_e32 v68, v68, v252
	v_mul_f32_e32 v69, v69, v252
	v_mul_f32_e32 v70, v70, v252
	v_mul_f32_e32 v71, v71, v252
	v_mul_f32_e32 v72, v72, v252
	v_mul_f32_e32 v73, v73, v252
	v_mul_f32_e32 v74, v74, v252
	v_mul_f32_e32 v75, v75, v252
	v_mul_f32_e32 v76, v76, v252
	v_mul_f32_e32 v77, v77, v252
	v_mul_f32_e32 v78, v78, v252
	v_mul_f32_e32 v79, v79, v252
	v_mul_f32_e32 v48, v48, v252
	v_mul_f32_e32 v49, v49, v252
	v_mul_f32_e32 v50, v50, v252
	v_mul_f32_e32 v51, v51, v252
	v_mul_f32_e32 v52, v52, v252
	v_mul_f32_e32 v53, v53, v252
	v_mul_f32_e32 v54, v54, v252
	v_mul_f32_e32 v55, v55, v252
	v_mul_f32_e32 v56, v56, v252
	v_mul_f32_e32 v57, v57, v252
	v_mul_f32_e32 v58, v58, v252
	v_mul_f32_e32 v59, v59, v252
	v_mul_f32_e32 v60, v60, v252
	v_mul_f32_e32 v61, v61, v252
	v_mul_f32_e32 v62, v62, v252
	v_mul_f32_e32 v63, v63, v252
	v_sub_f32_e32 v224, v224, v223
	v_sub_f32_e32 v225, v225, v223
	v_sub_f32_e32 v226, v226, v223
	v_sub_f32_e32 v227, v227, v223
	v_sub_f32_e32 v228, v228, v223
	v_sub_f32_e32 v229, v229, v223
	v_sub_f32_e32 v230, v230, v223
	v_sub_f32_e32 v231, v231, v223
	v_sub_f32_e32 v232, v232, v223
	v_sub_f32_e32 v233, v233, v223
	v_sub_f32_e32 v234, v234, v223
	v_sub_f32_e32 v235, v235, v223
	v_sub_f32_e32 v236, v236, v223
	v_sub_f32_e32 v237, v237, v223
	v_sub_f32_e32 v238, v238, v223
	v_sub_f32_e32 v239, v239, v223
	v_sub_f32_e32 v96, v96, v223
	v_sub_f32_e32 v97, v97, v223
	v_sub_f32_e32 v98, v98, v223
	v_sub_f32_e32 v99, v99, v223
	v_sub_f32_e32 v100, v100, v223
	v_sub_f32_e32 v101, v101, v223
	v_sub_f32_e32 v102, v102, v223
	v_sub_f32_e32 v103, v103, v223
	v_sub_f32_e32 v104, v104, v223
	v_sub_f32_e32 v105, v105, v223
	v_sub_f32_e32 v106, v106, v223
	v_sub_f32_e32 v107, v107, v223
	v_sub_f32_e32 v108, v108, v223
	v_sub_f32_e32 v109, v109, v223
	v_sub_f32_e32 v110, v110, v223
	v_sub_f32_e32 v111, v111, v223
	v_sub_f32_e32 v128, v128, v223
	v_sub_f32_e32 v129, v129, v223
	v_sub_f32_e32 v130, v130, v223
	v_sub_f32_e32 v131, v131, v223
	v_sub_f32_e32 v132, v132, v223
	v_sub_f32_e32 v133, v133, v223
	v_sub_f32_e32 v134, v134, v223
	v_sub_f32_e32 v135, v135, v223
	v_sub_f32_e32 v136, v136, v223
	v_sub_f32_e32 v137, v137, v223
	v_sub_f32_e32 v138, v138, v223
	v_sub_f32_e32 v139, v139, v223
	v_sub_f32_e32 v140, v140, v223
	v_sub_f32_e32 v141, v141, v223
	v_sub_f32_e32 v142, v142, v223
	v_sub_f32_e32 v143, v143, v223
	v_add_f32_e32 v221, v221, v223
	s_branch .LBB0_724
; DI unsigned pack2(float lo, float hi) { f2v_ f = {lo, hi}; b2v_ b = __builtin_convertvector(f, b2v_); return __builtin_bit_cast(unsigned, b); }
; #define MFMA32(a, b, c) __builtin_amdgcn_mfma_f32_32x32x16_bf16((a), (b), (c), 0, 0, 0)
; template <bool MLA, int DK, int DV>
; __device__ __forceinline__ void attn_core(const Params& p, int b, int h, int map, int q0, int nt, char* smem,
;                                           f32x16 (&o)[DV / 32], float& lout) {
;     ...
;     } else {
; #pragma unroll
;       for (int sub = 0; sub < 2; ++sub)
; #pragma unroll
;         for (int i = 0; i < 16; ++i) { const float x_ = __builtin_amdgcn_exp2f(fmaf(cur_[sub][i], sc, -mrun)); cur_[sub][i] = x_; psum += x_; }
;     }
;     lrun += psum;
;     bf16x8 pb[4];
; #pragma unroll
;     for (int kb = 0; kb < 4; ++kb) {
;       const int sub = kb >> 1, s8 = (kb & 1) * 8;
;       u32x4 pk;
;       pk.x = pack2(cur_[sub][s8 + 0], cur_[sub][s8 + 1]);
;       pk.y = pack2(cur_[sub][s8 + 2], cur_[sub][s8 + 3]);
;       pk.z = pack2(cur_[sub][s8 + 4], cur_[sub][s8 + 5]);
;       pk.w = pack2(cur_[sub][s8 + 6], cur_[sub][s8 + 7]);
;       pb[kb] = __builtin_bit_cast(bf16x8, pk);
;     }
;     float mx = -INFINITY;
; #pragma unroll
;     for (int hb = 0; hb < 2; ++hb) {
;       bf16x8 vf[2][NDVT];
; #pragma unroll
;       for (int q = 0; q < 2; ++q)
; #pragma unroll
;         for (int d = 0; d < NDVT; ++d) {
;           const bft* vp = Vc + (d * 32 + r) * VS_STRIDE + (hb * 2 + q) * 16 + 4 * h2;
;           const u32x2 lo = *(const u32x2*)vp, hi = *(const u32x2*)(vp + 8);
;           const u32x4 pa4 = {lo.x, lo.y, hi.x, hi.y};
;           vf[q][d] = __builtin_bit_cast(bf16x8, pa4);
;         }
; #pragma unroll
;       for (int q = 0; q < 2; ++q) {
;         const int kb = hb * 2 + q;
; #pragma unroll
;         for (int d = 0; d < NDVT; ++d) o[d] = MFMA32(vf[q][d], pb[kb], o[d]);
; #pragma unroll
;         for (int i = 0; i < 8; ++i) mx = fmaxf(mx, nxt_[kb >> 1][(kb & 1) * 8 + i]);
;       }
;     }
.Ld2b_cold:
	s_mov_b64 s[12:13], -1
	s_and_b64 vcc, exec, s[16:17]
	v_mov_b32_e32 v210, v112
	v_mov_b32_e32 v252, v113
	v_mov_b32_e32 v251, v114
	v_mov_b32_e32 v249, v115
	v_mov_b32_e32 v248, v116
	v_mov_b32_e32 v247, v117
	v_mov_b32_e32 v246, v118
	v_mov_b32_e32 v245, v119
	v_mov_b32_e32 v244, v120
	v_mov_b32_e32 v243, v121
	v_mov_b32_e32 v242, v122
	v_mov_b32_e32 v241, v123
	v_mov_b32_e32 v240, v124
	v_mov_b32_e32 v239, v125
	v_mov_b32_e32 v238, v126
	v_mov_b32_e32 v237, v127
	v_mov_b32_e32 v236, v144
	v_mov_b32_e32 v235, v145
	v_mov_b32_e32 v234, v146
	v_mov_b32_e32 v233, v147
	v_mov_b32_e32 v232, v148
	v_mov_b32_e32 v231, v149
	v_mov_b32_e32 v230, v150
	v_mov_b32_e32 v229, v151
	v_mov_b32_e32 v228, v152
	v_mov_b32_e32 v227, v153
	v_mov_b32_e32 v189, v154
	v_mov_b32_e32 v222, v155
	v_mov_b32_e32 v223, v156
	v_mov_b32_e32 v224, v157
	v_mov_b32_e32 v225, v158
	v_mov_b32_e32 v226, v159
	v_exp_f32_e32 v112, v210
	v_exp_f32_e32 v113, v252
	v_exp_f32_e32 v114, v251
	v_exp_f32_e32 v115, v249
	v_add_f32_e32 v116, 0, v112
	v_add_f32_e32 v116, v113, v116
	v_add_f32_e32 v116, v114, v116
	v_add_f32_e32 v120, v115, v116
	v_exp_f32_e32 v116, v248
	v_exp_f32_e32 v117, v247
	v_exp_f32_e32 v118, v246
	v_exp_f32_e32 v119, v245
	v_add_f32_e32 v120, v116, v120
	v_add_f32_e32 v120, v117, v120
	v_add_f32_e32 v120, v118, v120
	v_add_f32_e32 v124, v119, v120
	v_exp_f32_e32 v120, v244
	v_exp_f32_e32 v121, v243
	v_exp_f32_e32 v122, v242
	v_exp_f32_e32 v123, v241
	v_add_f32_e32 v124, v120, v124
	v_add_f32_e32 v124, v121, v124
	v_add_f32_e32 v124, v122, v124
	v_add_f32_e32 v144, v123, v124
	v_exp_f32_e32 v124, v240
	v_exp_f32_e32 v125, v239
	v_exp_f32_e32 v126, v238
	v_exp_f32_e32 v127, v237
	v_add_f32_e32 v144, v124, v144
	v_add_f32_e32 v144, v125, v144
	v_add_f32_e32 v144, v126, v144
	v_add_f32_e32 v148, v127, v144
	v_exp_f32_e32 v144, v236
	v_exp_f32_e32 v145, v235
	v_exp_f32_e32 v146, v234
	v_exp_f32_e32 v147, v233
	v_add_f32_e32 v148, v144, v148
	v_add_f32_e32 v148, v145, v148
	v_add_f32_e32 v148, v146, v148
	v_add_f32_e32 v152, v147, v148
	v_exp_f32_e32 v148, v232
	v_exp_f32_e32 v149, v231
	v_exp_f32_e32 v150, v230
	v_exp_f32_e32 v151, v229
	v_add_f32_e32 v152, v148, v152
	v_add_f32_e32 v152, v149, v152
	v_add_f32_e32 v152, v150, v152
	v_add_f32_e32 v156, v151, v152
	v_exp_f32_e32 v152, v228
	v_exp_f32_e32 v153, v227
	v_exp_f32_e32 v154, v189
	v_exp_f32_e32 v155, v222
	v_add_f32_e32 v156, v152, v156
	v_add_f32_e32 v156, v153, v156
	v_add_f32_e32 v156, v154, v156
	v_add_f32_e32 v198, v155, v156
	v_exp_f32_e32 v156, v223
	v_exp_f32_e32 v157, v224
	v_exp_f32_e32 v158, v225
	v_exp_f32_e32 v159, v226
	v_add_f32_e32 v198, v156, v198
	v_add_f32_e32 v198, v157, v198
	v_add_f32_e32 v198, v158, v198
	v_add_f32_e32 v250, v159, v198
	s_mov_b64 s[12:13], 0
.LBB0_721:
	v_add_u32_e32 v189, 0x9800, v219
	ds_read2_b64 v[222:225], v189 offset0:96 offset1:98
	v_cvt_pk_bf16_f32 v226, v112, v113
	v_cvt_pk_bf16_f32 v227, v114, v115
	v_cvt_pk_bf16_f32 v228, v116, v117
	v_cvt_pk_bf16_f32 v229, v118, v119
	v_add_u32_e32 v198, 0xa800, v219
	v_add_u32_e32 v199, 0xb800, v219
	v_add_f32_e32 v187, v187, v250
	s_andn2_b64 vcc, exec, s[14:15]
	s_waitcnt lgkmcnt(0)
	v_mfma_f32_32x32x16_bf16 v[80:95], v[222:225], v[226:229], v[80:95]
	ds_read2_b64 v[222:225], v198 offset0:128 offset1:130
	s_waitcnt lgkmcnt(0)
	v_mfma_f32_32x32x16_bf16 v[64:79], v[222:225], v[226:229], v[64:79]
	ds_read2_b64 v[222:225], v199 offset0:160 offset1:162
	s_waitcnt lgkmcnt(0)
	v_mfma_f32_32x32x16_bf16 v[48:63], v[222:225], v[226:229], v[48:63]
	ds_read2_b64 v[222:225], v189 offset0:100 offset1:102
	v_cvt_pk_bf16_f32 v226, v120, v121
	v_cvt_pk_bf16_f32 v227, v122, v123
	v_cvt_pk_bf16_f32 v228, v124, v125
	v_cvt_pk_bf16_f32 v229, v126, v127
	s_waitcnt lgkmcnt(0)
	s_nop 0
	v_mfma_f32_32x32x16_bf16 v[80:95], v[222:225], v[226:229], v[80:95]
	ds_read2_b64 v[222:225], v198 offset0:132 offset1:134
	s_waitcnt lgkmcnt(0)
	v_mfma_f32_32x32x16_bf16 v[64:79], v[222:225], v[226:229], v[64:79]
	ds_read2_b64 v[222:225], v199 offset0:164 offset1:166
	s_waitcnt lgkmcnt(0)
	v_mfma_f32_32x32x16_bf16 v[48:63], v[222:225], v[226:229], v[48:63]
	ds_read2_b64 v[222:225], v189 offset0:104 offset1:106
	v_cvt_pk_bf16_f32 v226, v144, v145
	v_cvt_pk_bf16_f32 v227, v146, v147
	v_cvt_pk_bf16_f32 v228, v148, v149
	v_cvt_pk_bf16_f32 v229, v150, v151
	s_waitcnt lgkmcnt(0)
	s_nop 0
	v_mfma_f32_32x32x16_bf16 v[80:95], v[222:225], v[226:229], v[80:95]
	ds_read2_b64 v[222:225], v198 offset0:136 offset1:138
	s_waitcnt lgkmcnt(0)
	v_mfma_f32_32x32x16_bf16 v[64:79], v[222:225], v[226:229], v[64:79]
	ds_read2_b64 v[222:225], v199 offset0:168 offset1:170
	s_waitcnt lgkmcnt(0)
	v_mfma_f32_32x32x16_bf16 v[48:63], v[222:225], v[226:229], v[48:63]
	ds_read2_b64 v[222:225], v189 offset0:108 offset1:110
	v_cvt_pk_bf16_f32 v226, v152, v153
	v_cvt_pk_bf16_f32 v227, v154, v155
	v_cvt_pk_bf16_f32 v228, v156, v157
	v_cvt_pk_bf16_f32 v229, v158, v159
	v_cndmask_b32_e64 v189, 0, 1, s[14:15]
	v_cmp_ne_u32_e64 s[12:13], 1, v189
	s_waitcnt lgkmcnt(0)
	v_mfma_f32_32x32x16_bf16 v[80:95], v[222:225], v[226:229], v[80:95]
	ds_read2_b64 v[222:225], v198 offset0:140 offset1:142
	s_waitcnt lgkmcnt(0)
	v_mfma_f32_32x32x16_bf16 v[64:79], v[222:225], v[226:229], v[64:79]
	ds_read2_b64 v[222:225], v199 offset0:172 offset1:174
	s_waitcnt lgkmcnt(0)
	v_mfma_f32_32x32x16_bf16 v[48:63], v[222:225], v[226:229], v[48:63]
	s_branch .LBB0_724

; DI unsigned pack2(float lo, float hi) { f2v_ f = {lo, hi}; b2v_ b = __builtin_convertvector(f, b2v_); return __builtin_bit_cast(unsigned, b); }
; __device__ __forceinline__ void diff_item(const Params& p, int layer, int b, int h, int qb, char* smem) {
;     ...
;     const float s = lam / l;
; #pragma unroll
;     for (int d = 0; d < 3; ++d)
; #pragma unroll
;       for (int i = 0; i < 8; ++i) o1p[d][i] = pack2(o[d][2 * i] * s, o[d][2 * i + 1] * s);
;   }
;   f32x16 o[3];
;   float l;
;   attn_core<false, 48, 96>(p, b, h, 0, q0, nt, smem, o, l);
;   const float i0 = 1.f / l;
;   float ssq = 0.f;
; #pragma unroll
;   for (int d = 0; d < 3; ++d)
; #pragma unroll
;     for (int i = 0; i < 8; ++i) {
;       const float a0 = o[d][2 * i] * i0 - __uint_as_float(o1p[d][i] << 16);
;       const float a1 = o[d][2 * i + 1] * i0 - __uint_as_float(o1p[d][i] & 0xffff0000u);
;       o[d][2 * i] = a0; o[d][2 * i + 1] = a1;
;       ssq += a0 * a0 + a1 * a1;
;     }
.LBB0_731:
	v_lshlrev_b32_e32 v96, 4, v196
	v_add_u32_e32 v96, 0xe000, v96
	ds_read_b128 v[0:3], v96
	ds_read_b128 v[4:7], v96 offset:8192
	ds_read_b128 v[8:11], v96 offset:16384
	ds_read_b128 v[12:15], v96 offset:24576
	ds_read_b128 v[16:19], v96 offset:32768
	ds_read_b128 v[20:23], v96 offset:40960
	s_waitcnt lgkmcnt(0)
	v_add_f32_e32 v96, v216, v217
	v_div_scale_f32 v97, s[6:7], v96, v96, v214
	v_rcp_f32_e32 v98, v97
	v_div_scale_f32 v99, vcc, v214, v96, v214
	v_fma_f32 v100, -v97, v98, 1.0
	v_fmac_f32_e32 v98, v100, v98
	v_mul_f32_e32 v100, v99, v98
	v_fma_f32 v101, -v97, v100, v99
	v_fmac_f32_e32 v100, v101, v98
	v_fma_f32 v97, -v97, v100, v99
	v_div_fmas_f32 v97, v97, v98, v100
	v_div_fixup_f32 v96, v97, v96, v214
	v_pk_mul_f32 v[36:37], v[36:37], v[96:97] op_sel_hi:[1,0]
	v_pk_mul_f32 v[46:47], v[46:47], v[96:97] op_sel_hi:[1,0]
	v_pk_mul_f32 v[44:45], v[44:45], v[96:97] op_sel_hi:[1,0]
	v_pk_mul_f32 v[42:43], v[42:43], v[96:97] op_sel_hi:[1,0]
	v_pk_mul_f32 v[40:41], v[40:41], v[96:97] op_sel_hi:[1,0]
	v_pk_mul_f32 v[38:39], v[38:39], v[96:97] op_sel_hi:[1,0]
	v_cvt_pk_bf16_f32 v97, v36, v37
	v_pk_mul_f32 v[10:11], v[10:11], v[96:97] op_sel_hi:[1,0]
	v_pk_mul_f32 v[8:9], v[8:9], v[96:97] op_sel_hi:[1,0]
	v_cvt_pk_bf16_f32 v10, v10, v11
	v_cvt_pk_bf16_f32 v11, v8, v9
	ds_bpermute_b32 v8, v215, v187
	v_pk_mul_f32 v[4:5], v[4:5], v[96:97] op_sel_hi:[1,0]
	v_pk_mul_f32 v[6:7], v[6:7], v[96:97] op_sel_hi:[1,0]
	v_cvt_pk_bf16_f32 v4, v4, v5
	v_cvt_pk_bf16_f32 v6, v6, v7
	s_waitcnt lgkmcnt(0)
	v_add_f32_e32 v5, v187, v8
	v_div_scale_f32 v7, s[6:7], v5, v5, 1.0
	v_rcp_f32_e32 v8, v7
	v_pk_mul_f32 v[0:1], v[0:1], v[96:97] op_sel_hi:[1,0]
	v_pk_mul_f32 v[2:3], v[2:3], v[96:97] op_sel_hi:[1,0]
	v_cvt_pk_bf16_f32 v0, v0, v1
	v_fma_f32 v1, -v7, v8, 1.0
	v_fmac_f32_e32 v8, v1, v8
	v_div_scale_f32 v1, vcc, 1.0, v5, 1.0
	v_cvt_pk_bf16_f32 v2, v2, v3
	v_mul_f32_e32 v3, v1, v8
	v_fma_f32 v9, -v7, v3, v1
	v_fmac_f32_e32 v3, v9, v8
	v_fma_f32 v1, -v7, v3, v1
	v_cvt_pk_bf16_f32 v102, v42, v43
	v_cvt_pk_bf16_f32 v103, v40, v41
	v_pk_mul_f32 v[26:27], v[26:27], v[96:97] op_sel_hi:[1,0]
	v_pk_mul_f32 v[14:15], v[14:15], v[96:97] op_sel_hi:[1,0]
	v_pk_mul_f32 v[12:13], v[12:13], v[96:97] op_sel_hi:[1,0]
	v_div_fmas_f32 v1, v1, v8, v3
	v_cvt_pk_bf16_f32 v99, v38, v39
	v_cvt_pk_bf16_f32 v39, v26, v27
	v_cvt_pk_bf16_f32 v27, v14, v15
	v_cvt_pk_bf16_f32 v13, v12, v13
	v_div_fixup_f32 v12, v1, v5, 1.0
	v_lshlrev_b32_e32 v14, 16, v0
	v_and_b32_e32 v15, 0xffff0000, v0
	v_lshlrev_b32_e32 v8, 16, v2
	v_and_b32_e32 v9, 0xffff0000, v2
	v_mov_b32_e32 v0, v58
	v_mov_b32_e32 v1, v56
	v_lshlrev_b32_e32 v3, 16, v103
	v_lshlrev_b32_e32 v2, 16, v102
	v_pk_mul_f32 v[30:31], v[30:31], v[96:97] op_sel_hi:[1,0]
	v_pk_mul_f32 v[18:19], v[18:19], v[96:97] op_sel_hi:[1,0]
	v_pk_fma_f32 v[2:3], v[0:1], v[12:13], v[2:3] op_sel_hi:[1,0,1] neg_lo:[0,0,1] neg_hi:[0,0,1]
	v_mov_b32_e32 v56, v59
	v_and_b32_e32 v1, 0xffff0000, v103
	v_and_b32_e32 v0, 0xffff0000, v102
	v_cvt_pk_bf16_f32 v43, v30, v31
	v_cvt_pk_bf16_f32 v31, v18, v19
	v_lshlrev_b32_e32 v18, 16, v6
	v_and_b32_e32 v19, 0xffff0000, v6
	v_pk_fma_f32 v[6:7], v[56:57], v[12:13], v[0:1] op_sel_hi:[1,0,1] neg_lo:[0,0,1] neg_hi:[0,0,1]
	v_cvt_pk_bf16_f32 v100, v46, v47
	v_cvt_pk_bf16_f32 v101, v44, v45
	v_pk_mul_f32 v[28:29], v[28:29], v[96:97] op_sel_hi:[1,0]
	v_pk_mul_f32 v[16:17], v[16:17], v[96:97] op_sel_hi:[1,0]
	v_pk_mul_f32 v[0:1], v[6:7], v[6:7]
	v_cvt_pk_bf16_f32 v41, v28, v29
	v_cvt_pk_bf16_f32 v29, v16, v17
	v_lshlrev_b32_e32 v16, 16, v4
	v_and_b32_e32 v17, 0xffff0000, v4
	v_pk_fma_f32 v[56:57], v[2:3], v[2:3], v[0:1]
	v_mov_b32_e32 v0, v62
	v_mov_b32_e32 v1, v60
	v_lshlrev_b32_e32 v5, 16, v101
	v_lshlrev_b32_e32 v4, 16, v100
	v_pk_fma_f32 v[0:1], v[0:1], v[12:13], v[4:5] op_sel_hi:[1,0,1] neg_lo:[0,0,1] neg_hi:[0,0,1]
	v_mov_b32_e32 v60, v63
	v_and_b32_e32 v5, 0xffff0000, v101
	v_and_b32_e32 v4, 0xffff0000, v100
	v_pk_mul_f32 v[34:35], v[34:35], v[96:97] op_sel_hi:[1,0]
	v_pk_mul_f32 v[32:33], v[32:33], v[96:97] op_sel_hi:[1,0]
	v_pk_mul_f32 v[22:23], v[22:23], v[96:97] op_sel_hi:[1,0]
	v_pk_mul_f32 v[20:21], v[20:21], v[96:97] op_sel_hi:[1,0]
	v_pk_fma_f32 v[4:5], v[60:61], v[12:13], v[4:5] op_sel_hi:[1,0,1] neg_lo:[0,0,1] neg_hi:[0,0,1]
	v_cvt_pk_bf16_f32 v47, v34, v35
	v_cvt_pk_bf16_f32 v45, v32, v33
	v_cvt_pk_bf16_f32 v35, v22, v23
	v_cvt_pk_bf16_f32 v33, v20, v21
	v_lshlrev_b32_e32 v20, 16, v11
	v_and_b32_e32 v21, 0xffff0000, v11
	v_lshlrev_b32_e32 v22, 16, v10
	v_and_b32_e32 v23, 0xffff0000, v10
	v_pk_mul_f32 v[10:11], v[4:5], v[4:5]
	v_pk_fma_f32 v[60:61], v[82:83], v[12:13], v[8:9] op_sel_hi:[1,0,1] neg_lo:[0,0,1] neg_hi:[0,0,1]
	v_pk_fma_f32 v[58:59], v[0:1], v[0:1], v[10:11]
	v_ashrrev_i32_e32 v10, 1, v213
	v_and_b32_e32 v10, 0xffffffe0, v10
	v_add_u32_e32 v100, s39, v10
	v_lshrrev_b32_e32 v10, 3, v212
	v_and_b32_e32 v101, 4, v10
	v_lshlrev_b32_e32 v102, 2, v101
	global_load_dwordx4 v[8:11], v102, s[42:43]
	v_lshlrev_b32_e32 v44, 16, v45
	v_and_b32_e32 v45, 0xffff0000, v45
	v_lshlrev_b32_e32 v46, 16, v47
	v_and_b32_e32 v47, 0xffff0000, v47
	v_pk_mul_f32 v[24:25], v[24:25], v[96:97] op_sel_hi:[1,0]
	v_pk_fma_f32 v[46:47], v[50:51], v[12:13], v[46:47] op_sel_hi:[1,0,1] neg_lo:[0,0,1] neg_hi:[0,0,1]
	v_pk_fma_f32 v[44:45], v[48:49], v[12:13], v[44:45] op_sel_hi:[1,0,1] neg_lo:[0,0,1] neg_hi:[0,0,1]
	v_cvt_pk_bf16_f32 v37, v24, v25
	v_mov_b32_e32 v50, v47
	v_mov_b32_e32 v51, v45
	v_lshlrev_b32_e32 v24, 16, v13
	v_and_b32_e32 v25, 0xffff0000, v13
	v_lshlrev_b32_e32 v26, 16, v27
	v_and_b32_e32 v27, 0xffff0000, v27
	v_lshlrev_b32_e32 v28, 16, v29
	v_and_b32_e32 v29, 0xffff0000, v29
	v_lshlrev_b32_e32 v30, 16, v31
; __device__ __forceinline__ void diff_item(const Params& p, int layer, int b, int h, int qb, char* smem) {
;     ...
;   const float i0 = 1.f / l;
;   float ssq = 0.f;
; #pragma unroll
;   for (int d = 0; d < 3; ++d)
; #pragma unroll
;     for (int i = 0; i < 8; ++i) {
;       const float a0 = o[d][2 * i] * i0 - __uint_as_float(o1p[d][i] << 16);
;       const float a1 = o[d][2 * i + 1] * i0 - __uint_as_float(o1p[d][i] & 0xffff0000u);
;       o[d][2 * i] = a0; o[d][2 * i + 1] = a1;
;       ssq += a0 * a0 + a1 * a1;
;     }
;   ssq += __shfl_xor(ssq, 32);
;   const float rn = rsqrtf(ssq * (1.f / 96.f) + LN_EPS) * (1.f - lam_init);
;   const float* sub = p.in[I_SUBLN] + layer * 96;
	v_and_b32_e32 v31, 0xffff0000, v31
	v_lshlrev_b32_e32 v32, 16, v33
	v_and_b32_e32 v33, 0xffff0000, v33
	v_lshlrev_b32_e32 v34, 16, v35
	v_and_b32_e32 v35, 0xffff0000, v35
	v_lshlrev_b32_e32 v36, 16, v37
	v_and_b32_e32 v37, 0xffff0000, v37
	v_lshlrev_b32_e32 v38, 16, v39
	v_and_b32_e32 v39, 0xffff0000, v39
	v_lshlrev_b32_e32 v40, 16, v41
	v_and_b32_e32 v41, 0xffff0000, v41
	v_lshlrev_b32_e32 v42, 16, v43
	v_and_b32_e32 v43, 0xffff0000, v43
	v_lshlrev_b32_e32 v96, 16, v97
	v_and_b32_e32 v97, 0xffff0000, v97
	v_lshlrev_b32_e32 v98, 16, v99
	v_and_b32_e32 v99, 0xffff0000, v99
	v_mov_b32_e32 v48, v46
	v_mov_b32_e32 v49, v44
	v_pk_mul_f32 v[50:51], v[50:51], v[50:51]
	v_pk_fma_f32 v[14:15], v[80:81], v[12:13], v[14:15] op_sel_hi:[1,0,1] neg_lo:[0,0,1] neg_hi:[0,0,1]
	v_pk_fma_f32 v[18:19], v[86:87], v[12:13], v[18:19] op_sel_hi:[1,0,1] neg_lo:[0,0,1] neg_hi:[0,0,1]
	v_pk_fma_f32 v[16:17], v[84:85], v[12:13], v[16:17] op_sel_hi:[1,0,1] neg_lo:[0,0,1] neg_hi:[0,0,1]
	v_pk_fma_f32 v[22:23], v[90:91], v[12:13], v[22:23] op_sel_hi:[1,0,1] neg_lo:[0,0,1] neg_hi:[0,0,1]
	v_pk_fma_f32 v[20:21], v[88:89], v[12:13], v[20:21] op_sel_hi:[1,0,1] neg_lo:[0,0,1] neg_hi:[0,0,1]
	v_pk_fma_f32 v[26:27], v[94:95], v[12:13], v[26:27] op_sel_hi:[1,0,1] neg_lo:[0,0,1] neg_hi:[0,0,1]
	v_pk_fma_f32 v[24:25], v[92:93], v[12:13], v[24:25] op_sel_hi:[1,0,1] neg_lo:[0,0,1] neg_hi:[0,0,1]
	v_pk_fma_f32 v[30:31], v[66:67], v[12:13], v[30:31] op_sel_hi:[1,0,1] neg_lo:[0,0,1] neg_hi:[0,0,1]
	v_pk_fma_f32 v[28:29], v[64:65], v[12:13], v[28:29] op_sel_hi:[1,0,1] neg_lo:[0,0,1] neg_hi:[0,0,1]
	v_pk_fma_f32 v[34:35], v[70:71], v[12:13], v[34:35] op_sel_hi:[1,0,1] neg_lo:[0,0,1] neg_hi:[0,0,1]
	v_pk_fma_f32 v[32:33], v[68:69], v[12:13], v[32:33] op_sel_hi:[1,0,1] neg_lo:[0,0,1] neg_hi:[0,0,1]
	v_pk_fma_f32 v[38:39], v[74:75], v[12:13], v[38:39] op_sel_hi:[1,0,1] neg_lo:[0,0,1] neg_hi:[0,0,1]
	v_pk_fma_f32 v[36:37], v[72:73], v[12:13], v[36:37] op_sel_hi:[1,0,1] neg_lo:[0,0,1] neg_hi:[0,0,1]
	v_pk_fma_f32 v[42:43], v[78:79], v[12:13], v[42:43] op_sel_hi:[1,0,1] neg_lo:[0,0,1] neg_hi:[0,0,1]
	v_pk_fma_f32 v[40:41], v[76:77], v[12:13], v[40:41] op_sel_hi:[1,0,1] neg_lo:[0,0,1] neg_hi:[0,0,1]
	v_pk_fma_f32 v[48:49], v[48:49], v[48:49], v[50:51]
	v_pk_fma_f32 v[50:51], v[54:55], v[12:13], v[98:99] op_sel_hi:[1,0,1] neg_lo:[0,0,1] neg_hi:[0,0,1]
	v_pk_fma_f32 v[12:13], v[52:53], v[12:13], v[96:97] op_sel_hi:[1,0,1] neg_lo:[0,0,1] neg_hi:[0,0,1]
	v_mov_b32_e32 v54, v51
	v_mov_b32_e32 v55, v13
	v_pk_mul_f32 v[62:63], v[60:61], v[60:61]
	v_pk_mul_f32 v[80:81], v[14:15], v[14:15]
	v_mov_b32_e32 v52, v50
	v_mov_b32_e32 v53, v12
	v_pk_mul_f32 v[54:55], v[54:55], v[54:55]
	v_pk_mul_f32 v[84:85], v[16:17], v[16:17]
	v_pk_fma_f32 v[52:53], v[52:53], v[52:53], v[54:55]
	v_add_f32_e32 v54, v62, v63
	v_add_f32_e32 v55, v80, v81
	v_pk_mul_f32 v[82:83], v[18:19], v[18:19]
	v_add_f32_e32 v54, v55, v54
	v_add_f32_e32 v55, v84, v85
	v_pk_mul_f32 v[88:89], v[20:21], v[20:21]
	v_add_f32_e32 v54, v55, v54
	v_add_f32_e32 v55, v82, v83
	v_pk_mul_f32 v[86:87], v[22:23], v[22:23]
	v_add_f32_e32 v54, v55, v54
	v_add_f32_e32 v55, v88, v89
	v_pk_mul_f32 v[92:93], v[24:25], v[24:25]
	v_add_f32_e32 v54, v55, v54
	v_add_f32_e32 v55, v86, v87
	v_pk_mul_f32 v[90:91], v[26:27], v[26:27]
	v_add_f32_e32 v54, v55, v54
	v_add_f32_e32 v55, v92, v93
	v_pk_mul_f32 v[64:65], v[28:29], v[28:29]
	v_add_f32_e32 v54, v55, v54
	v_add_f32_e32 v55, v90, v91
	v_pk_mul_f32 v[66:67], v[30:31], v[30:31]
	v_add_f32_e32 v54, v55, v54
	v_add_f32_e32 v55, v64, v65
	v_pk_mul_f32 v[68:69], v[32:33], v[32:33]
	v_add_f32_e32 v54, v55, v54
	v_add_f32_e32 v55, v66, v67
	v_pk_mul_f32 v[70:71], v[34:35], v[34:35]
	v_add_f32_e32 v54, v55, v54
	v_add_f32_e32 v55, v68, v69
	v_pk_mul_f32 v[72:73], v[36:37], v[36:37]
	v_add_f32_e32 v54, v55, v54
	v_add_f32_e32 v55, v70, v71
	v_pk_mul_f32 v[74:75], v[38:39], v[38:39]
	v_mov_b32_e32 v78, v43
	v_mov_b32_e32 v79, v41
	v_add_f32_e32 v54, v55, v54
	v_add_f32_e32 v55, v72, v73
	v_mov_b32_e32 v76, v42
	v_mov_b32_e32 v77, v40
	v_pk_mul_f32 v[78:79], v[78:79], v[78:79]
	v_add_f32_e32 v54, v55, v54
	v_add_f32_e32 v55, v74, v75
	v_pk_fma_f32 v[76:77], v[76:77], v[76:77], v[78:79]
	v_add_f32_e32 v54, v55, v54
	v_add_f32_e32 v54, v77, v54
	v_add_f32_e32 v54, v76, v54
	v_add_f32_e32 v49, v49, v54
	v_add_f32_e32 v48, v48, v49
	v_add_f32_e32 v48, v53, v48
	v_add_f32_e32 v48, v52, v48
	v_add_f32_e32 v48, v57, v48
	v_add_f32_e32 v48, v56, v48
	v_add_f32_e32 v48, v59, v48
	v_add_f32_e32 v52, v58, v48
	ds_bpermute_b32 v53, v215, v52
	v_and_or_b32 v48, v212, 31, v100
	v_ashrrev_i32_e32 v49, 31, v48
	v_lshlrev_b64 v[48:49], 11, v[48:49]
	v_lshl_add_u64 v[48:49], s[90:91], 0, v[48:49]
	s_waitcnt lgkmcnt(0)
	v_add_f32_e32 v52, v52, v53
	v_fmamk_f32 v52, v52, 0x3c2aaaab, v206
	v_mul_f32_e32 v53, 0x4b800000, v52
	v_cmp_gt_f32_e32 vcc, s52, v52
	v_lshl_add_u64 v[48:49], s[48:49], 1, v[48:49]
	v_lshlrev_b32_e32 v160, 1, v101
	v_cndmask_b32_e32 v52, v52, v53, vcc
	v_rsq_f32_e32 v52, v52
	v_lshl_add_u64 v[48:49], v[48:49], 0, v[160:161]
	s_mov_b32 s6, 0x11000000
	v_mov_b32_e32 v214, v200
	v_mul_f32_e32 v53, 0x45800000, v52
	v_cndmask_b32_e32 v52, v52, v53, vcc
	v_mul_f32_e32 v52, v211, v52
	v_pk_mul_f32 v[14:15], v[14:15], v[52:53] op_sel_hi:[1,0]
	v_pk_mul_f32 v[16:17], v[16:17], v[52:53] op_sel_hi:[1,0]
	s_waitcnt vmcnt(0)
; DI unsigned pack2(float lo, float hi) { f2v_ f = {lo, hi}; b2v_ b = __builtin_convertvector(f, b2v_); return __builtin_bit_cast(unsigned, b); }
; __device__ __forceinline__ void diff_item(const Params& p, int layer, int b, int h, int qb, char* smem) {
;     ...
;   const float* sub = p.in[I_SUBLN] + layer * 96;
;   bft* O = (bft*)(p.ws + OFF_XN);
;   const int orow = b * NTOK + q0 + wave * 32 + r;
; #pragma unroll
;   for (int d = 0; d < 3; ++d)
; #pragma unroll
;     for (int i4 = 0; i4 < 4; ++i4) {
;       const int dv = d * 32 + 8 * i4 + 4 * h2;
;       const float4 g = *(const float4*)(sub + dv);
;       u32x2 w;
;       w.x = pack2(o[d][i4 * 4 + 0] * rn * g.x, o[d][i4 * 4 + 1] * rn * g.y);
;       w.y = pack2(o[d][i4 * 4 + 2] * rn * g.z, o[d][i4 * 4 + 3] * rn * g.w);
;       *(u32x2*)(O + (size_t)orow * D + 384 + h * 96 + dv) = w;
;     }
	v_pk_mul_f32 v[8:9], v[8:9], v[14:15]
	v_pk_mul_f32 v[14:15], v[60:61], v[52:53] op_sel_hi:[1,0]
	v_cvt_pk_bf16_f32 v8, v8, v9
	v_pk_mul_f32 v[10:11], v[10:11], v[14:15]
	v_pk_mul_f32 v[12:13], v[12:13], v[52:53] op_sel_hi:[1,0]
	v_cvt_pk_bf16_f32 v9, v10, v11
	v_add_co_u32_e32 v10, vcc, s6, v48
	s_mov_b64 s[6:7], 0x11000300
	s_nop 0
	v_addc_co_u32_e32 v11, vcc, 0, v49, vcc
	global_store_dwordx2 v[10:11], v[8:9], off offset:768
	global_load_dwordx4 v[8:11], v102, s[42:43] offset:32
	v_lshl_add_u64 v[14:15], v[48:49], 0, s[6:7]
	s_waitcnt vmcnt(0)
	v_pk_mul_f32 v[8:9], v[8:9], v[16:17]
	v_pk_mul_f32 v[16:17], v[18:19], v[52:53] op_sel_hi:[1,0]
	v_cvt_pk_bf16_f32 v8, v8, v9
	v_pk_mul_f32 v[10:11], v[10:11], v[16:17]
	v_pk_mul_f32 v[16:17], v[20:21], v[52:53] op_sel_hi:[1,0]
	v_cvt_pk_bf16_f32 v9, v10, v11
	global_store_dwordx2 v[14:15], v[8:9], off offset:16
	global_load_dwordx4 v[8:11], v102, s[42:43] offset:64
	v_pk_mul_f32 v[18:19], v[26:27], v[52:53] op_sel_hi:[1,0]
	s_waitcnt vmcnt(0)
	v_pk_mul_f32 v[8:9], v[8:9], v[16:17]
	v_pk_mul_f32 v[16:17], v[22:23], v[52:53] op_sel_hi:[1,0]
	v_cvt_pk_bf16_f32 v8, v8, v9
	v_pk_mul_f32 v[10:11], v[10:11], v[16:17]
	v_pk_mul_f32 v[16:17], v[24:25], v[52:53] op_sel_hi:[1,0]
	v_cvt_pk_bf16_f32 v9, v10, v11
	global_store_dwordx2 v[14:15], v[8:9], off offset:32
	global_load_dwordx4 v[8:11], v102, s[42:43] offset:96
	s_waitcnt vmcnt(0)
	v_pk_mul_f32 v[8:9], v[8:9], v[16:17]
	v_pk_mul_f32 v[10:11], v[10:11], v[18:19]
	v_cvt_pk_bf16_f32 v8, v8, v9
	v_cvt_pk_bf16_f32 v9, v10, v11
	global_store_dwordx2 v[14:15], v[8:9], off offset:48
	global_load_dwordx4 v[8:11], v102, s[42:43] offset:128
	v_pk_mul_f32 v[16:17], v[28:29], v[52:53] op_sel_hi:[1,0]
	v_pk_mul_f32 v[18:19], v[30:31], v[52:53] op_sel_hi:[1,0]
	s_waitcnt vmcnt(0)
	v_pk_mul_f32 v[8:9], v[8:9], v[16:17]
	v_pk_mul_f32 v[10:11], v[10:11], v[18:19]
	v_cvt_pk_bf16_f32 v8, v8, v9
	v_cvt_pk_bf16_f32 v9, v10, v11
	global_store_dwordx2 v[14:15], v[8:9], off offset:64
	global_load_dwordx4 v[8:11], v102, s[42:43] offset:160
	v_pk_mul_f32 v[16:17], v[32:33], v[52:53] op_sel_hi:[1,0]
	v_pk_mul_f32 v[18:19], v[34:35], v[52:53] op_sel_hi:[1,0]
	s_waitcnt vmcnt(0)
	v_pk_mul_f32 v[8:9], v[8:9], v[16:17]
	v_pk_mul_f32 v[10:11], v[10:11], v[18:19]
	v_cvt_pk_bf16_f32 v8, v8, v9
	v_cvt_pk_bf16_f32 v9, v10, v11
	global_store_dwordx2 v[14:15], v[8:9], off offset:80
	global_load_dwordx4 v[8:11], v102, s[42:43] offset:192
	v_pk_mul_f32 v[16:17], v[36:37], v[52:53] op_sel_hi:[1,0]
	v_pk_mul_f32 v[18:19], v[38:39], v[52:53] op_sel_hi:[1,0]
	s_waitcnt vmcnt(0)
	v_pk_mul_f32 v[8:9], v[8:9], v[16:17]
	v_pk_mul_f32 v[10:11], v[10:11], v[18:19]
	v_cvt_pk_bf16_f32 v8, v8, v9
	v_cvt_pk_bf16_f32 v9, v10, v11
	global_store_dwordx2 v[14:15], v[8:9], off offset:96
	global_load_dwordx4 v[8:11], v102, s[42:43] offset:224
	v_pk_mul_f32 v[16:17], v[40:41], v[52:53] op_sel_hi:[1,0]
	v_pk_mul_f32 v[18:19], v[42:43], v[52:53] op_sel_hi:[1,0]
	s_waitcnt vmcnt(0)
	v_pk_mul_f32 v[8:9], v[8:9], v[16:17]
	v_pk_mul_f32 v[10:11], v[10:11], v[18:19]
	v_cvt_pk_bf16_f32 v8, v8, v9
	v_cvt_pk_bf16_f32 v9, v10, v11
	global_store_dwordx2 v[14:15], v[8:9], off offset:112
	global_load_dwordx4 v[8:11], v102, s[42:43] offset:256
	v_pk_mul_f32 v[16:17], v[44:45], v[52:53] op_sel_hi:[1,0]
	v_pk_mul_f32 v[18:19], v[46:47], v[52:53] op_sel_hi:[1,0]
	s_waitcnt vmcnt(0)
	v_pk_mul_f32 v[8:9], v[16:17], v[8:9]
	v_pk_mul_f32 v[10:11], v[18:19], v[10:11]
	v_cvt_pk_bf16_f32 v8, v8, v9
	v_cvt_pk_bf16_f32 v9, v10, v11
	global_store_dwordx2 v[14:15], v[8:9], off offset:128
	global_load_dwordx4 v[8:11], v102, s[42:43] offset:288
	v_pk_mul_f32 v[16:17], v[50:51], v[52:53] op_sel_hi:[1,0]
	s_waitcnt vmcnt(0)
	v_pk_mul_f32 v[8:9], v[12:13], v[8:9]
	v_pk_mul_f32 v[10:11], v[16:17], v[10:11]
	v_cvt_pk_bf16_f32 v8, v8, v9
	v_cvt_pk_bf16_f32 v9, v10, v11
	global_store_dwordx2 v[14:15], v[8:9], off offset:144
	global_load_dwordx4 v[8:11], v102, s[42:43] offset:320
	v_mov_b32_e32 v12, v3
	v_mov_b32_e32 v13, v7
	v_mov_b32_e32 v3, v6
	v_pk_mul_f32 v[6:7], v[12:13], v[52:53] op_sel_hi:[1,0]
	v_pk_mul_f32 v[2:3], v[2:3], v[52:53] op_sel_hi:[1,0]
	s_waitcnt vmcnt(0)
	v_pk_mul_f32 v[6:7], v[6:7], v[8:9]
	v_pk_mul_f32 v[2:3], v[2:3], v[10:11]
	v_cvt_pk_bf16_f32 v6, v6, v7
	v_cvt_pk_bf16_f32 v7, v2, v3
	global_store_dwordx2 v[14:15], v[6:7], off offset:160
	global_load_dwordx4 v[6:9], v102, s[42:43] offset:352
	v_mov_b32_e32 v2, v1
	v_mov_b32_e32 v3, v5
	v_mov_b32_e32 v1, v4
	v_pk_mul_f32 v[2:3], v[2:3], v[52:53] op_sel_hi:[1,0]
	v_pk_mul_f32 v[0:1], v[0:1], v[52:53] op_sel_hi:[1,0]
	s_waitcnt vmcnt(0)
	v_pk_mul_f32 v[2:3], v[2:3], v[6:7]
	v_pk_mul_f32 v[0:1], v[0:1], v[8:9]
	v_cvt_pk_bf16_f32 v2, v2, v3
	v_cvt_pk_bf16_f32 v3, v0, v1
	global_store_dwordx2 v[14:15], v[2:3], off offset:176
